# peeled first K-loop iteration with C=0 (no accumulator zeroing) on 4 K-loops; packed-fma SwiGLU epilogue
# speedup vs baseline: 1.0285x; 1.0121x over previous
; #define PG8_STAGE(bufoff, gbase, voff) do { _Pragma("unroll") for (int _i = 0; _i < 2; ++_i) { \
;         const unsigned _m0 = ldsb + (unsigned)((bufoff) + _i * 8192); const char* _gb = (const char*)(gbase); \
;         asm volatile("s_mov_b32 m0, %0\n\ts_nop 0\n\tglobal_load_lds_dwordx4 %1, %2" :: "s"(_m0), "v"((voff)[_i]), "s"(_gb) : "m0", "memory"); } } while (0)
; #define PG8_LDA(dst, b, h) do { _Pragma("unroll") for (int m = 0; m < 4; ++m) _Pragma("unroll") for (int k = 0; k < 2; ++k) dst[m][k] = *(const LAS bf16x8*)(lds + PG8_SA(b, h) + aoff + m * 2048 + k * 1024); } while (0)
; #define PG8_LDB(dst, b, h) do { _Pragma("unroll") for (int n = 0; n < 2; ++n) _Pragma("unroll") for (int k = 0; k < 2; ++k) dst[n][k] = *(const LAS bf16x8*)(lds + PG8_SB(b, h) + boff + n * 2048 + k * 1024); } while (0)
; #define PG8_MMA(ai, bj, At, Bt) do { __builtin_amdgcn_s_setprio(1); _Pragma("unroll") for (int m = 0; m < 4; ++m) _Pragma("unroll") for (int n = 0; n < 2; ++n) _Pragma("unroll") for (int k = 0; k < 2; ++k) \
;         acc[ai][bj][m][n] = __builtin_amdgcn_mfma_f32_16x16x32_bf16(Bt[n][k], At[m][k], acc[ai][bj][m][n], 0, 0, 0); __builtin_amdgcn_s_setprio(0); } while (0)
; #define PG8_WAIT_V(n) asm volatile("s_waitcnt vmcnt(" #n ")" ::: "memory")
; #define PG8_WAIT_L(n) asm volatile("s_waitcnt lgkmcnt(" #n ")" ::: "memory")
; template <class Epi, bool ALIGN_EPI>
; __device__ __forceinline__ void gemm_phase(LAS unsigned char* lds, const Gemm g, const StaticOrder& S, const Epi& E) {
;     ...
;         for (int t = 0; t < nt; t += 2) {
;             const bool last = (t == nt - 2);
;             const char* a1 = cA + (size_t)(t + 1) * kstep;
;             const char* a2 = last ? nA : cA + (size_t)(t + 2) * kstep; const char* b2 = last ? nB : cB + (size_t)(t + 2) * kstep;
;             const char* a3 = a2 + kstep; const char* b3 = b2 + kstep;
;             PG8_LDB(B0, 0, 0); PG8_LDB(B1, 0, 1); PG8_SCHED; PG8_LDA(At, 0, 0); PG8_STAGE(PG8_SA(1, 1), a1 + hstepA, voffA);
;             PG8_WAIT_V(8); PG8_WAIT_L(0); PG8_BAR; PG8_MMA(0, 0, At, B0); PG8_MMA(0, 1, At, B1); PG8_BAR; PG8_SCHED;
;             PG8_LDA(At, 0, 1); PG8_STAGE(PG8_SB(0, 0), b2, voffB); PG8_STAGE(PG8_SB(0, 1), b2 + hstepB, voffB); PG8_STAGE(PG8_SA(0, 0), a2, voffA);
;             PG8_WAIT_V(8); PG8_WAIT_L(0); PG8_BAR; PG8_MMA(1, 0, At, B0); PG8_MMA(1, 1, At, B1); PG8_BAR; PG8_SCHED;
.LBB0_150:
	s_add_u32 s4, s48, 0x100
	s_addc_u32 s5, s49, 0
	s_add_u32 s37, s54, 0x100
	s_addc_u32 s44, s55, 0
	s_mov_b32 s45, 0
	s_waitcnt lgkmcnt(0)
	v_add_u32_e32 v132, 0x10000, v244
	v_add_u32_e32 v152, 0x14000, v244
	ds_read_b128 v[108:111], v132
	ds_read_b128 v[120:123], v132 offset:1024
	ds_read_b128 v[128:131], v132 offset:2048
	ds_read_b128 v[132:135], v132 offset:3072
	ds_read_b128 v[136:139], v152
	ds_read_b128 v[144:147], v152 offset:1024
	ds_read_b128 v[148:151], v152 offset:2048
	ds_read_b128 v[152:155], v152 offset:3072
	s_add_i32 s51, s45, 2
	s_cmp_eq_u32 s67, s45
	s_cselect_b32 s56, s0, s37
	s_cselect_b32 s57, s1, s44
	s_cselect_b32 s54, s94, s4
	s_cselect_b32 s55, s95, s5
	s_add_u32 s48, s56, 0x80
	s_addc_u32 s49, s57, 0
	ds_read_b128 v[156:159], v245
	ds_read_b128 v[160:163], v245 offset:1024
	ds_read_b128 v[164:167], v245 offset:2048
	ds_read_b128 v[176:179], v245 offset:3072
	ds_read_b128 v[180:183], v245 offset:4096
	ds_read_b128 v[184:187], v245 offset:5120
	ds_read_b128 v[188:191], v245 offset:6144
	ds_read_b128 v[202:205], v245 offset:7168
	s_add_u32 s45, s37, s15
	s_addc_u32 s59, s44, 0
	s_add_u32 s58, s45, 0xffffff80
	s_addc_u32 s59, s59, -1
	s_mov_b32 m0, s68
	s_nop 0
	global_load_lds_dwordx4 v0, s[58:59]
	s_nop 0
	s_mov_b32 m0, s85
	s_nop 0
	global_load_lds_dwordx4 v240, s[58:59]
	s_waitcnt vmcnt(8)
	s_waitcnt lgkmcnt(0)
	s_barrier
	s_setprio 1
	s_waitcnt lgkmcnt(0)
	v_mfma_f32_16x16x32_bf16 v[172:175], v[108:111], v[156:159], 0
	v_mfma_f32_16x16x32_bf16 v[172:175], v[120:123], v[160:163], v[172:175]
	v_mfma_f32_16x16x32_bf16 v[168:171], v[128:131], v[156:159], 0
	v_mfma_f32_16x16x32_bf16 v[168:171], v[132:135], v[160:163], v[168:171]
	v_mfma_f32_16x16x32_bf16 v[140:143], v[136:139], v[156:159], 0
	v_mfma_f32_16x16x32_bf16 v[140:143], v[144:147], v[160:163], v[140:143]
	v_mfma_f32_16x16x32_bf16 v[124:127], v[148:151], v[156:159], 0
	v_mfma_f32_16x16x32_bf16 v[124:127], v[152:155], v[160:163], v[124:127]
	v_mfma_f32_16x16x32_bf16 v[100:103], v[148:151], v[164:167], 0
	v_mfma_f32_16x16x32_bf16 v[100:103], v[152:155], v[176:179], v[100:103]
	v_mfma_f32_16x16x32_bf16 v[104:107], v[136:139], v[164:167], 0
	v_mfma_f32_16x16x32_bf16 v[104:107], v[144:147], v[176:179], v[104:107]
	v_mfma_f32_16x16x32_bf16 v[112:115], v[128:131], v[164:167], 0
	v_mfma_f32_16x16x32_bf16 v[112:115], v[132:135], v[176:179], v[112:115]
	v_mfma_f32_16x16x32_bf16 v[116:119], v[108:111], v[164:167], 0
	v_mfma_f32_16x16x32_bf16 v[116:119], v[120:123], v[176:179], v[116:119]
	v_mfma_f32_16x16x32_bf16 v[96:99], v[108:111], v[180:183], 0
	v_mfma_f32_16x16x32_bf16 v[96:99], v[120:123], v[184:187], v[96:99]
	v_mfma_f32_16x16x32_bf16 v[92:95], v[128:131], v[180:183], 0
	v_mfma_f32_16x16x32_bf16 v[92:95], v[132:135], v[184:187], v[92:95]
	v_mfma_f32_16x16x32_bf16 v[88:91], v[136:139], v[180:183], 0
	v_mfma_f32_16x16x32_bf16 v[88:91], v[144:147], v[184:187], v[88:91]
	v_mfma_f32_16x16x32_bf16 v[84:87], v[148:151], v[180:183], 0
	v_mfma_f32_16x16x32_bf16 v[84:87], v[152:155], v[184:187], v[84:87]
	v_mfma_f32_16x16x32_bf16 v[68:71], v[148:151], v[188:191], 0
	v_mfma_f32_16x16x32_bf16 v[68:71], v[152:155], v[202:205], v[68:71]
	v_mfma_f32_16x16x32_bf16 v[72:75], v[136:139], v[188:191], 0
	v_mfma_f32_16x16x32_bf16 v[72:75], v[144:147], v[202:205], v[72:75]
	v_mfma_f32_16x16x32_bf16 v[76:79], v[128:131], v[188:191], 0
	v_mfma_f32_16x16x32_bf16 v[76:79], v[132:135], v[202:205], v[76:79]
	v_mfma_f32_16x16x32_bf16 v[80:83], v[108:111], v[188:191], 0
	v_mfma_f32_16x16x32_bf16 v[80:83], v[120:123], v[202:205], v[80:83]
	s_setprio 0
	s_barrier
	ds_read_b128 v[156:159], v245 offset:16384
	ds_read_b128 v[160:163], v245 offset:17408
	ds_read_b128 v[164:167], v245 offset:18432
	ds_read_b128 v[176:179], v245 offset:19456
	ds_read_b128 v[180:183], v245 offset:20480
	ds_read_b128 v[184:187], v245 offset:21504
	ds_read_b128 v[188:191], v245 offset:22528
	ds_read_b128 v[202:205], v245 offset:23552
	s_mov_b32 m0, s27
	s_nop 0
	global_load_lds_dwordx4 v195, s[54:55]
	s_add_u32 s58, s54, s15
	s_mov_b32 m0, s28
	s_nop 0
	global_load_lds_dwordx4 v241, s[54:55]
	s_addc_u32 s59, s55, 0
	s_mov_b32 m0, s29
	s_nop 0
	global_load_lds_dwordx4 v195, s[58:59]
	s_nop 0
	s_mov_b32 m0, s30
	s_nop 0
	global_load_lds_dwordx4 v241, s[58:59]
	s_nop 0
	s_mov_b32 m0, s26
	s_nop 0
	global_load_lds_dwordx4 v0, s[56:57]
	s_nop 0
	s_mov_b32 m0, s31
	s_nop 0
	global_load_lds_dwordx4 v240, s[56:57]
	s_waitcnt vmcnt(8)
	s_waitcnt lgkmcnt(0)
	s_barrier
	s_setprio 1
	s_waitcnt lgkmcnt(0)
	v_mfma_f32_16x16x32_bf16 v[64:67], v[108:111], v[156:159], 0
	v_mfma_f32_16x16x32_bf16 v[64:67], v[120:123], v[160:163], v[64:67]
	v_mfma_f32_16x16x32_bf16 v[60:63], v[128:131], v[156:159], 0
	v_mfma_f32_16x16x32_bf16 v[60:63], v[132:135], v[160:163], v[60:63]
	v_mfma_f32_16x16x32_bf16 v[56:59], v[136:139], v[156:159], 0
	v_mfma_f32_16x16x32_bf16 v[56:59], v[144:147], v[160:163], v[56:59]
	v_mfma_f32_16x16x32_bf16 v[52:55], v[148:151], v[156:159], 0
	v_mfma_f32_16x16x32_bf16 v[52:55], v[152:155], v[160:163], v[52:55]
	v_mfma_f32_16x16x32_bf16 v[36:39], v[148:151], v[164:167], 0
	v_mfma_f32_16x16x32_bf16 v[36:39], v[152:155], v[176:179], v[36:39]
	v_mfma_f32_16x16x32_bf16 v[40:43], v[136:139], v[164:167], 0
	v_mfma_f32_16x16x32_bf16 v[40:43], v[144:147], v[176:179], v[40:43]
	v_mfma_f32_16x16x32_bf16 v[44:47], v[128:131], v[164:167], 0
	v_mfma_f32_16x16x32_bf16 v[44:47], v[132:135], v[176:179], v[44:47]
	v_mfma_f32_16x16x32_bf16 v[48:51], v[108:111], v[164:167], 0
	v_mfma_f32_16x16x32_bf16 v[48:51], v[120:123], v[176:179], v[48:51]
	v_mfma_f32_16x16x32_bf16 v[32:35], v[108:111], v[180:183], 0
	v_mfma_f32_16x16x32_bf16 v[32:35], v[120:123], v[184:187], v[32:35]
	v_mfma_f32_16x16x32_bf16 v[28:31], v[128:131], v[180:183], 0
	v_mfma_f32_16x16x32_bf16 v[28:31], v[132:135], v[184:187], v[28:31]
	v_mfma_f32_16x16x32_bf16 v[24:27], v[136:139], v[180:183], 0
	v_mfma_f32_16x16x32_bf16 v[24:27], v[144:147], v[184:187], v[24:27]
	v_mfma_f32_16x16x32_bf16 v[20:23], v[148:151], v[180:183], 0
	v_mfma_f32_16x16x32_bf16 v[20:23], v[152:155], v[184:187], v[20:23]
	v_mfma_f32_16x16x32_bf16 v[4:7], v[148:151], v[188:191], 0
	v_mfma_f32_16x16x32_bf16 v[4:7], v[152:155], v[202:205], v[4:7]
	v_mfma_f32_16x16x32_bf16 v[8:11], v[136:139], v[188:191], 0
	v_mfma_f32_16x16x32_bf16 v[8:11], v[144:147], v[202:205], v[8:11]
	v_mfma_f32_16x16x32_bf16 v[12:15], v[128:131], v[188:191], 0
	v_mfma_f32_16x16x32_bf16 v[12:15], v[132:135], v[202:205], v[12:15]
	v_mfma_f32_16x16x32_bf16 v[16:19], v[108:111], v[188:191], 0
	v_mfma_f32_16x16x32_bf16 v[16:19], v[120:123], v[202:205], v[16:19]
	s_setprio 0
	s_barrier
; #define PG8_STAGE(bufoff, gbase, voff) do { _Pragma("unroll") for (int _i = 0; _i < 2; ++_i) { \
;         const unsigned _m0 = ldsb + (unsigned)((bufoff) + _i * 8192); const char* _gb = (const char*)(gbase); \
;         asm volatile("s_mov_b32 m0, %0\n\ts_nop 0\n\tglobal_load_lds_dwordx4 %1, %2" :: "s"(_m0), "v"((voff)[_i]), "s"(_gb) : "m0", "memory"); } } while (0)
; #define PG8_LDA(dst, b, h) do { _Pragma("unroll") for (int m = 0; m < 4; ++m) _Pragma("unroll") for (int k = 0; k < 2; ++k) dst[m][k] = *(const LAS bf16x8*)(lds + PG8_SA(b, h) + aoff + m * 2048 + k * 1024); } while (0)
; #define PG8_LDB(dst, b, h) do { _Pragma("unroll") for (int n = 0; n < 2; ++n) _Pragma("unroll") for (int k = 0; k < 2; ++k) dst[n][k] = *(const LAS bf16x8*)(lds + PG8_SB(b, h) + boff + n * 2048 + k * 1024); } while (0)
; #define PG8_MMA(ai, bj, At, Bt) do { __builtin_amdgcn_s_setprio(1); _Pragma("unroll") for (int m = 0; m < 4; ++m) _Pragma("unroll") for (int n = 0; n < 2; ++n) _Pragma("unroll") for (int k = 0; k < 2; ++k) \
;         acc[ai][bj][m][n] = __builtin_amdgcn_mfma_f32_16x16x32_bf16(Bt[n][k], At[m][k], acc[ai][bj][m][n], 0, 0, 0); __builtin_amdgcn_s_setprio(0); } while (0)
; #define PG8_WAIT_V(n) asm volatile("s_waitcnt vmcnt(" #n ")" ::: "memory")
; #define PG8_WAIT_L(n) asm volatile("s_waitcnt lgkmcnt(" #n ")" ::: "memory")
; #define PG8_BAR __builtin_amdgcn_s_barrier()
; #define PG8_SCHED __builtin_amdgcn_sched_barrier(0)
; template <class Epi, bool ALIGN_EPI>
; __device__ __forceinline__ void gemm_phase(LAS unsigned char* lds, const Gemm g, const StaticOrder& S, const Epi& E) {
;     ...
;             PG8_LDB(B0, 1, 0); PG8_LDB(B1, 1, 1); PG8_SCHED; PG8_LDA(At, 1, 0); PG8_STAGE(PG8_SA(0, 1), a2 + hstepA, voffA);
;             PG8_WAIT_V(8); PG8_WAIT_L(0); PG8_BAR; PG8_MMA(0, 0, At, B0); PG8_MMA(0, 1, At, B1); PG8_BAR; PG8_SCHED;
;             PG8_LDA(At, 1, 1); PG8_STAGE(PG8_SB(1, 0), b3, voffB); PG8_STAGE(PG8_SB(1, 1), b3 + hstepB, voffB); PG8_STAGE(PG8_SA(1, 0), a3, voffA);
;             PG8_WAIT_V(8); PG8_WAIT_L(0); PG8_BAR; PG8_MMA(1, 0, At, B0); PG8_MMA(1, 1, At, B1); PG8_BAR; PG8_SCHED;
;         }
	v_add_u32_e32 v132, 0x18000, v244
	v_add_u32_e32 v152, 0x1c000, v244
	ds_read_b128 v[108:111], v132
	ds_read_b128 v[120:123], v132 offset:1024
	ds_read_b128 v[128:131], v132 offset:2048
	ds_read_b128 v[132:135], v132 offset:3072
	ds_read_b128 v[136:139], v152
	ds_read_b128 v[144:147], v152 offset:1024
	ds_read_b128 v[148:151], v152 offset:2048
	ds_read_b128 v[152:155], v152 offset:3072
	ds_read_b128 v[156:159], v245 offset:32768
	ds_read_b128 v[160:163], v245 offset:33792
	ds_read_b128 v[164:167], v245 offset:34816
	ds_read_b128 v[176:179], v245 offset:35840
	ds_read_b128 v[180:183], v245 offset:36864
	ds_read_b128 v[184:187], v245 offset:37888
	ds_read_b128 v[188:191], v245 offset:38912
	ds_read_b128 v[202:205], v245 offset:39936
	s_add_u32 s56, s56, s15
	s_addc_u32 s57, s57, 0
	s_mov_b32 m0, s41
	s_nop 0
	global_load_lds_dwordx4 v0, s[56:57]
	s_nop 0
	s_mov_b32 m0, s42
	s_nop 0
	global_load_lds_dwordx4 v240, s[56:57]
	s_waitcnt vmcnt(8)
	s_waitcnt lgkmcnt(0)
	s_barrier
	s_setprio 1
	s_waitcnt lgkmcnt(0)
	v_mfma_f32_16x16x32_bf16 v[172:175], v[108:111], v[156:159], v[172:175]
	v_mfma_f32_16x16x32_bf16 v[172:175], v[120:123], v[160:163], v[172:175]
	v_mfma_f32_16x16x32_bf16 v[168:171], v[128:131], v[156:159], v[168:171]
	v_mfma_f32_16x16x32_bf16 v[168:171], v[132:135], v[160:163], v[168:171]
	v_mfma_f32_16x16x32_bf16 v[140:143], v[136:139], v[156:159], v[140:143]
	v_mfma_f32_16x16x32_bf16 v[140:143], v[144:147], v[160:163], v[140:143]
	v_mfma_f32_16x16x32_bf16 v[124:127], v[148:151], v[156:159], v[124:127]
	v_mfma_f32_16x16x32_bf16 v[124:127], v[152:155], v[160:163], v[124:127]
	v_mfma_f32_16x16x32_bf16 v[100:103], v[148:151], v[164:167], v[100:103]
	v_mfma_f32_16x16x32_bf16 v[100:103], v[152:155], v[176:179], v[100:103]
	v_mfma_f32_16x16x32_bf16 v[104:107], v[136:139], v[164:167], v[104:107]
	v_mfma_f32_16x16x32_bf16 v[104:107], v[144:147], v[176:179], v[104:107]
	v_mfma_f32_16x16x32_bf16 v[112:115], v[128:131], v[164:167], v[112:115]
	v_mfma_f32_16x16x32_bf16 v[112:115], v[132:135], v[176:179], v[112:115]
	v_mfma_f32_16x16x32_bf16 v[116:119], v[108:111], v[164:167], v[116:119]
	v_mfma_f32_16x16x32_bf16 v[116:119], v[120:123], v[176:179], v[116:119]
	v_mfma_f32_16x16x32_bf16 v[96:99], v[108:111], v[180:183], v[96:99]
	v_mfma_f32_16x16x32_bf16 v[96:99], v[120:123], v[184:187], v[96:99]
	v_mfma_f32_16x16x32_bf16 v[92:95], v[128:131], v[180:183], v[92:95]
	v_mfma_f32_16x16x32_bf16 v[92:95], v[132:135], v[184:187], v[92:95]
	v_mfma_f32_16x16x32_bf16 v[88:91], v[136:139], v[180:183], v[88:91]
	v_mfma_f32_16x16x32_bf16 v[88:91], v[144:147], v[184:187], v[88:91]
	v_mfma_f32_16x16x32_bf16 v[84:87], v[148:151], v[180:183], v[84:87]
	v_mfma_f32_16x16x32_bf16 v[84:87], v[152:155], v[184:187], v[84:87]
	v_mfma_f32_16x16x32_bf16 v[68:71], v[148:151], v[188:191], v[68:71]
	v_mfma_f32_16x16x32_bf16 v[68:71], v[152:155], v[202:205], v[68:71]
	v_mfma_f32_16x16x32_bf16 v[72:75], v[136:139], v[188:191], v[72:75]
	v_mfma_f32_16x16x32_bf16 v[72:75], v[144:147], v[202:205], v[72:75]
	v_mfma_f32_16x16x32_bf16 v[76:79], v[128:131], v[188:191], v[76:79]
	v_mfma_f32_16x16x32_bf16 v[76:79], v[132:135], v[202:205], v[76:79]
	v_mfma_f32_16x16x32_bf16 v[80:83], v[108:111], v[188:191], v[80:83]
	v_mfma_f32_16x16x32_bf16 v[80:83], v[120:123], v[202:205], v[80:83]
	s_setprio 0
	s_barrier
	ds_read_b128 v[156:159], v245 offset:49152
	ds_read_b128 v[160:163], v245 offset:50176
	ds_read_b128 v[164:167], v245 offset:51200
	ds_read_b128 v[176:179], v245 offset:52224
	ds_read_b128 v[180:183], v245 offset:53248
	ds_read_b128 v[184:187], v245 offset:54272
	ds_read_b128 v[188:191], v245 offset:55296
	ds_read_b128 v[202:205], v245 offset:56320
	s_add_u32 s54, s54, 0x80
	s_addc_u32 s55, s55, 0
	s_mov_b32 m0, s46
	s_nop 0
	global_load_lds_dwordx4 v195, s[54:55]
	s_nop 0
	s_mov_b32 m0, s50
	s_nop 0
	global_load_lds_dwordx4 v241, s[54:55]
	s_add_u32 s54, s58, 0x80
	s_addc_u32 s55, s59, 0
	s_mov_b32 m0, s61
	s_nop 0
	global_load_lds_dwordx4 v195, s[54:55]
	s_nop 0
	s_mov_b32 m0, s65
	s_nop 0
	global_load_lds_dwordx4 v241, s[54:55]
	s_nop 0
	s_mov_b32 m0, s53
	s_nop 0
	global_load_lds_dwordx4 v0, s[48:49]
	s_nop 0
	s_mov_b32 m0, s60
	s_nop 0
	global_load_lds_dwordx4 v240, s[48:49]
	s_waitcnt vmcnt(8)
	s_waitcnt lgkmcnt(0)
	s_barrier
	s_setprio 1
	s_waitcnt lgkmcnt(0)
	v_mfma_f32_16x16x32_bf16 v[64:67], v[108:111], v[156:159], v[64:67]
	v_mfma_f32_16x16x32_bf16 v[64:67], v[120:123], v[160:163], v[64:67]
	v_mfma_f32_16x16x32_bf16 v[60:63], v[128:131], v[156:159], v[60:63]
	v_mfma_f32_16x16x32_bf16 v[60:63], v[132:135], v[160:163], v[60:63]
	v_mfma_f32_16x16x32_bf16 v[56:59], v[136:139], v[156:159], v[56:59]
	v_mfma_f32_16x16x32_bf16 v[56:59], v[144:147], v[160:163], v[56:59]
	v_mfma_f32_16x16x32_bf16 v[52:55], v[148:151], v[156:159], v[52:55]
	v_mfma_f32_16x16x32_bf16 v[52:55], v[152:155], v[160:163], v[52:55]
	v_mfma_f32_16x16x32_bf16 v[36:39], v[148:151], v[164:167], v[36:39]
	v_mfma_f32_16x16x32_bf16 v[36:39], v[152:155], v[176:179], v[36:39]
	v_mfma_f32_16x16x32_bf16 v[40:43], v[136:139], v[164:167], v[40:43]
	v_mfma_f32_16x16x32_bf16 v[40:43], v[144:147], v[176:179], v[40:43]
	v_mfma_f32_16x16x32_bf16 v[44:47], v[128:131], v[164:167], v[44:47]
	v_mfma_f32_16x16x32_bf16 v[44:47], v[132:135], v[176:179], v[44:47]
	v_mfma_f32_16x16x32_bf16 v[48:51], v[108:111], v[164:167], v[48:51]
	v_mfma_f32_16x16x32_bf16 v[48:51], v[120:123], v[176:179], v[48:51]
	v_mfma_f32_16x16x32_bf16 v[32:35], v[108:111], v[180:183], v[32:35]
	v_mfma_f32_16x16x32_bf16 v[32:35], v[120:123], v[184:187], v[32:35]
	v_mfma_f32_16x16x32_bf16 v[28:31], v[128:131], v[180:183], v[28:31]
	v_mfma_f32_16x16x32_bf16 v[28:31], v[132:135], v[184:187], v[28:31]
	v_mfma_f32_16x16x32_bf16 v[24:27], v[136:139], v[180:183], v[24:27]
	v_mfma_f32_16x16x32_bf16 v[24:27], v[144:147], v[184:187], v[24:27]
	v_mfma_f32_16x16x32_bf16 v[20:23], v[148:151], v[180:183], v[20:23]
	v_mfma_f32_16x16x32_bf16 v[20:23], v[152:155], v[184:187], v[20:23]
	v_mfma_f32_16x16x32_bf16 v[4:7], v[148:151], v[188:191], v[4:7]
	v_mfma_f32_16x16x32_bf16 v[4:7], v[152:155], v[202:205], v[4:7]
	v_mfma_f32_16x16x32_bf16 v[8:11], v[136:139], v[188:191], v[8:11]
	v_mfma_f32_16x16x32_bf16 v[8:11], v[144:147], v[202:205], v[8:11]
	v_mfma_f32_16x16x32_bf16 v[12:15], v[128:131], v[188:191], v[12:15]
	v_mfma_f32_16x16x32_bf16 v[12:15], v[132:135], v[202:205], v[12:15]
	v_mfma_f32_16x16x32_bf16 v[16:19], v[108:111], v[188:191], v[16:19]
	v_mfma_f32_16x16x32_bf16 v[16:19], v[120:123], v[202:205], v[16:19]
	s_setprio 0
	s_barrier
	s_add_u32 s4, s4, 0x100
	s_addc_u32 s5, s5, 0
	s_add_u32 s37, s37, 0x100
	s_addc_u32 s44, s44, 0
	s_cmp_ge_u32 s51, s43
	s_mov_b32 s45, s51

; #define PG8_STAGE(bufoff, gbase, voff) do { _Pragma("unroll") for (int _i = 0; _i < 2; ++_i) { \
;         const unsigned _m0 = ldsb + (unsigned)((bufoff) + _i * 8192); const char* _gb = (const char*)(gbase); \
;         asm volatile("s_mov_b32 m0, %0\n\ts_nop 0\n\tglobal_load_lds_dwordx4 %1, %2" :: "s"(_m0), "v"((voff)[_i]), "s"(_gb) : "m0", "memory"); } } while (0)
; #define PG8_LDA(dst, b, h) do { _Pragma("unroll") for (int m = 0; m < 4; ++m) _Pragma("unroll") for (int k = 0; k < 2; ++k) dst[m][k] = *(const LAS bf16x8*)(lds + PG8_SA(b, h) + aoff + m * 2048 + k * 1024); } while (0)
; #define PG8_LDB(dst, b, h) do { _Pragma("unroll") for (int n = 0; n < 2; ++n) _Pragma("unroll") for (int k = 0; k < 2; ++k) dst[n][k] = *(const LAS bf16x8*)(lds + PG8_SB(b, h) + boff + n * 2048 + k * 1024); } while (0)
; #define PG8_MMA(ai, bj, At, Bt) do { __builtin_amdgcn_s_setprio(1); _Pragma("unroll") for (int m = 0; m < 4; ++m) _Pragma("unroll") for (int n = 0; n < 2; ++n) _Pragma("unroll") for (int k = 0; k < 2; ++k) \
;         acc[ai][bj][m][n] = __builtin_amdgcn_mfma_f32_16x16x32_bf16(Bt[n][k], At[m][k], acc[ai][bj][m][n], 0, 0, 0); __builtin_amdgcn_s_setprio(0); } while (0)
; #define PG8_WAIT_V(n) asm volatile("s_waitcnt vmcnt(" #n ")" ::: "memory")
; #define PG8_WAIT_L(n) asm volatile("s_waitcnt lgkmcnt(" #n ")" ::: "memory")
; template <class Epi, bool ALIGN_EPI>
; __device__ __forceinline__ void gemm_phase(LAS unsigned char* lds, const Gemm g, const StaticOrder& S, const Epi& E) {
;     ...
;         for (int t = 0; t < nt; t += 2) {
;             const bool last = (t == nt - 2);
;             const char* a1 = cA + (size_t)(t + 1) * kstep;
;             const char* a2 = last ? nA : cA + (size_t)(t + 2) * kstep; const char* b2 = last ? nB : cB + (size_t)(t + 2) * kstep;
;             const char* a3 = a2 + kstep; const char* b3 = b2 + kstep;
;             PG8_LDB(B0, 0, 0); PG8_LDB(B1, 0, 1); PG8_SCHED; PG8_LDA(At, 0, 0); PG8_STAGE(PG8_SA(1, 1), a1 + hstepA, voffA);
;             PG8_WAIT_V(8); PG8_WAIT_L(0); PG8_BAR; PG8_MMA(0, 0, At, B0); PG8_MMA(0, 1, At, B1); PG8_BAR; PG8_SCHED;
;             PG8_LDA(At, 0, 1); PG8_STAGE(PG8_SB(0, 0), b2, voffB); PG8_STAGE(PG8_SB(0, 1), b2 + hstepB, voffB); PG8_STAGE(PG8_SA(0, 0), a2, voffA);
;             PG8_WAIT_V(8); PG8_WAIT_L(0); PG8_BAR; PG8_MMA(1, 0, At, B0); PG8_MMA(1, 1, At, B1); PG8_BAR; PG8_SCHED;
.LBB0_200:
	s_add_u32 s4, s48, 0x100
	s_addc_u32 s5, s49, 0
	s_add_u32 s15, s54, 0x100
	s_addc_u32 s42, s55, 0
	s_mov_b32 s43, 0
	v_add_u32_e32 v142, 0x10000, v245
	v_add_u32_e32 v158, 0x14000, v245
	ds_read_b128 v[130:133], v142
	ds_read_b128 v[134:137], v142 offset:1024
	ds_read_b128 v[138:141], v142 offset:2048
	ds_read_b128 v[142:145], v142 offset:3072
	ds_read_b128 v[146:149], v158
	ds_read_b128 v[150:153], v158 offset:1024
	ds_read_b128 v[154:157], v158 offset:2048
	ds_read_b128 v[158:161], v158 offset:3072
	s_add_i32 s44, s43, 2
	s_cmp_eq_u32 s68, s43
	s_cselect_b32 s56, s0, s15
	s_cselect_b32 s57, s1, s42
	s_cselect_b32 s54, s94, s4
	s_cselect_b32 s55, s95, s5
	s_add_u32 s48, s56, 0x80
	s_addc_u32 s49, s57, 0
	ds_read_b128 v[162:165], v246
	ds_read_b128 v[166:169], v246 offset:1024
	ds_read_b128 v[170:173], v246 offset:2048
	ds_read_b128 v[174:177], v246 offset:3072
	ds_read_b128 v[178:181], v246 offset:4096
	ds_read_b128 v[182:185], v246 offset:5120
	ds_read_b128 v[186:189], v246 offset:6144
	ds_read_b128 v[190:193], v246 offset:7168
	s_add_u32 s43, s15, s38
	s_addc_u32 s45, s42, 0
	s_add_u32 s58, s43, 0xffffff80
	s_addc_u32 s59, s45, -1
	s_mov_b32 m0, s37
	s_nop 0
	global_load_lds_dwordx4 v0, s[58:59]
	s_nop 0
	s_mov_b32 m0, s41
	s_nop 0
	global_load_lds_dwordx4 v206, s[58:59]
	s_waitcnt vmcnt(8)
	s_waitcnt lgkmcnt(0)
	s_barrier
	s_setprio 1
	s_waitcnt lgkmcnt(0)
	v_mfma_f32_16x16x32_bf16 v[126:129], v[130:133], v[162:165], 0
	v_mfma_f32_16x16x32_bf16 v[126:129], v[134:137], v[166:169], v[126:129]
	v_mfma_f32_16x16x32_bf16 v[122:125], v[138:141], v[162:165], 0
	v_mfma_f32_16x16x32_bf16 v[122:125], v[142:145], v[166:169], v[122:125]
	v_mfma_f32_16x16x32_bf16 v[118:121], v[146:149], v[162:165], 0
	v_mfma_f32_16x16x32_bf16 v[118:121], v[150:153], v[166:169], v[118:121]
	v_mfma_f32_16x16x32_bf16 v[114:117], v[154:157], v[162:165], 0
	v_mfma_f32_16x16x32_bf16 v[114:117], v[158:161], v[166:169], v[114:117]
	v_mfma_f32_16x16x32_bf16 v[98:101], v[154:157], v[170:173], 0
	v_mfma_f32_16x16x32_bf16 v[98:101], v[158:161], v[174:177], v[98:101]
	v_mfma_f32_16x16x32_bf16 v[102:105], v[146:149], v[170:173], 0
	v_mfma_f32_16x16x32_bf16 v[102:105], v[150:153], v[174:177], v[102:105]
	v_mfma_f32_16x16x32_bf16 v[106:109], v[138:141], v[170:173], 0
	v_mfma_f32_16x16x32_bf16 v[106:109], v[142:145], v[174:177], v[106:109]
	v_mfma_f32_16x16x32_bf16 v[110:113], v[130:133], v[170:173], 0
	v_mfma_f32_16x16x32_bf16 v[110:113], v[134:137], v[174:177], v[110:113]
	v_mfma_f32_16x16x32_bf16 v[94:97], v[130:133], v[178:181], 0
	v_mfma_f32_16x16x32_bf16 v[94:97], v[134:137], v[182:185], v[94:97]
	v_mfma_f32_16x16x32_bf16 v[90:93], v[138:141], v[178:181], 0
	v_mfma_f32_16x16x32_bf16 v[90:93], v[142:145], v[182:185], v[90:93]
	v_mfma_f32_16x16x32_bf16 v[86:89], v[146:149], v[178:181], 0
	v_mfma_f32_16x16x32_bf16 v[86:89], v[150:153], v[182:185], v[86:89]
	v_mfma_f32_16x16x32_bf16 v[82:85], v[154:157], v[178:181], 0
	v_mfma_f32_16x16x32_bf16 v[82:85], v[158:161], v[182:185], v[82:85]
	v_mfma_f32_16x16x32_bf16 v[66:69], v[154:157], v[186:189], 0
	v_mfma_f32_16x16x32_bf16 v[66:69], v[158:161], v[190:193], v[66:69]
	v_mfma_f32_16x16x32_bf16 v[70:73], v[146:149], v[186:189], 0
	v_mfma_f32_16x16x32_bf16 v[70:73], v[150:153], v[190:193], v[70:73]
	v_mfma_f32_16x16x32_bf16 v[74:77], v[138:141], v[186:189], 0
	v_mfma_f32_16x16x32_bf16 v[74:77], v[142:145], v[190:193], v[74:77]
	v_mfma_f32_16x16x32_bf16 v[78:81], v[130:133], v[186:189], 0
	v_mfma_f32_16x16x32_bf16 v[78:81], v[134:137], v[190:193], v[78:81]
	s_setprio 0
	s_barrier
	ds_read_b128 v[162:165], v246 offset:16384
	ds_read_b128 v[166:169], v246 offset:17408
	ds_read_b128 v[170:173], v246 offset:18432
	ds_read_b128 v[174:177], v246 offset:19456
	ds_read_b128 v[178:181], v246 offset:20480
	ds_read_b128 v[182:185], v246 offset:21504
	ds_read_b128 v[186:189], v246 offset:22528
	ds_read_b128 v[190:193], v246 offset:23552
	s_mov_b32 m0, s46
	s_nop 0
	global_load_lds_dwordx4 v195, s[54:55]
	s_add_u32 s58, s54, s38
	s_mov_b32 m0, s26
	s_nop 0
	global_load_lds_dwordx4 v207, s[54:55]
	s_addc_u32 s59, s55, 0
	s_mov_b32 m0, s27
	s_nop 0
	global_load_lds_dwordx4 v195, s[58:59]
	s_nop 0
	s_mov_b32 m0, s30
	s_nop 0
	global_load_lds_dwordx4 v207, s[58:59]
	s_nop 0
	s_mov_b32 m0, s29
	s_nop 0
	global_load_lds_dwordx4 v0, s[56:57]
	s_nop 0
	s_mov_b32 m0, s17
	s_nop 0
	global_load_lds_dwordx4 v206, s[56:57]
	s_waitcnt vmcnt(8)
	s_waitcnt lgkmcnt(0)
	s_barrier
	s_setprio 1
	s_waitcnt lgkmcnt(0)
	v_mfma_f32_16x16x32_bf16 v[62:65], v[130:133], v[162:165], 0
	v_mfma_f32_16x16x32_bf16 v[62:65], v[134:137], v[166:169], v[62:65]
	v_mfma_f32_16x16x32_bf16 v[58:61], v[138:141], v[162:165], 0
	v_mfma_f32_16x16x32_bf16 v[58:61], v[142:145], v[166:169], v[58:61]
	v_mfma_f32_16x16x32_bf16 v[54:57], v[146:149], v[162:165], 0
	v_mfma_f32_16x16x32_bf16 v[54:57], v[150:153], v[166:169], v[54:57]
	v_mfma_f32_16x16x32_bf16 v[50:53], v[154:157], v[162:165], 0
	v_mfma_f32_16x16x32_bf16 v[50:53], v[158:161], v[166:169], v[50:53]
	v_mfma_f32_16x16x32_bf16 v[34:37], v[154:157], v[170:173], 0
	v_mfma_f32_16x16x32_bf16 v[34:37], v[158:161], v[174:177], v[34:37]
	v_mfma_f32_16x16x32_bf16 v[38:41], v[146:149], v[170:173], 0
	v_mfma_f32_16x16x32_bf16 v[38:41], v[150:153], v[174:177], v[38:41]
	v_mfma_f32_16x16x32_bf16 v[42:45], v[138:141], v[170:173], 0
	v_mfma_f32_16x16x32_bf16 v[42:45], v[142:145], v[174:177], v[42:45]
	v_mfma_f32_16x16x32_bf16 v[46:49], v[130:133], v[170:173], 0
	v_mfma_f32_16x16x32_bf16 v[46:49], v[134:137], v[174:177], v[46:49]
	v_mfma_f32_16x16x32_bf16 v[30:33], v[130:133], v[178:181], 0
	v_mfma_f32_16x16x32_bf16 v[30:33], v[134:137], v[182:185], v[30:33]
	v_mfma_f32_16x16x32_bf16 v[26:29], v[138:141], v[178:181], 0
	v_mfma_f32_16x16x32_bf16 v[26:29], v[142:145], v[182:185], v[26:29]
	v_mfma_f32_16x16x32_bf16 v[22:25], v[146:149], v[178:181], 0
	v_mfma_f32_16x16x32_bf16 v[22:25], v[150:153], v[182:185], v[22:25]
	v_mfma_f32_16x16x32_bf16 v[18:21], v[154:157], v[178:181], 0
	v_mfma_f32_16x16x32_bf16 v[18:21], v[158:161], v[182:185], v[18:21]
	v_mfma_f32_16x16x32_bf16 v[2:5], v[154:157], v[186:189], 0
	v_mfma_f32_16x16x32_bf16 v[2:5], v[158:161], v[190:193], v[2:5]
	v_mfma_f32_16x16x32_bf16 v[6:9], v[146:149], v[186:189], 0
	v_mfma_f32_16x16x32_bf16 v[6:9], v[150:153], v[190:193], v[6:9]
	v_mfma_f32_16x16x32_bf16 v[10:13], v[138:141], v[186:189], 0
	v_mfma_f32_16x16x32_bf16 v[10:13], v[142:145], v[190:193], v[10:13]
	v_mfma_f32_16x16x32_bf16 v[14:17], v[130:133], v[186:189], 0
	v_mfma_f32_16x16x32_bf16 v[14:17], v[134:137], v[190:193], v[14:17]
	s_setprio 0
	s_barrier
; #define PG8_STAGE(bufoff, gbase, voff) do { _Pragma("unroll") for (int _i = 0; _i < 2; ++_i) { \
;         const unsigned _m0 = ldsb + (unsigned)((bufoff) + _i * 8192); const char* _gb = (const char*)(gbase); \
;         asm volatile("s_mov_b32 m0, %0\n\ts_nop 0\n\tglobal_load_lds_dwordx4 %1, %2" :: "s"(_m0), "v"((voff)[_i]), "s"(_gb) : "m0", "memory"); } } while (0)
; #define PG8_LDA(dst, b, h) do { _Pragma("unroll") for (int m = 0; m < 4; ++m) _Pragma("unroll") for (int k = 0; k < 2; ++k) dst[m][k] = *(const LAS bf16x8*)(lds + PG8_SA(b, h) + aoff + m * 2048 + k * 1024); } while (0)
; #define PG8_LDB(dst, b, h) do { _Pragma("unroll") for (int n = 0; n < 2; ++n) _Pragma("unroll") for (int k = 0; k < 2; ++k) dst[n][k] = *(const LAS bf16x8*)(lds + PG8_SB(b, h) + boff + n * 2048 + k * 1024); } while (0)
; #define PG8_MMA(ai, bj, At, Bt) do { __builtin_amdgcn_s_setprio(1); _Pragma("unroll") for (int m = 0; m < 4; ++m) _Pragma("unroll") for (int n = 0; n < 2; ++n) _Pragma("unroll") for (int k = 0; k < 2; ++k) \
;         acc[ai][bj][m][n] = __builtin_amdgcn_mfma_f32_16x16x32_bf16(Bt[n][k], At[m][k], acc[ai][bj][m][n], 0, 0, 0); __builtin_amdgcn_s_setprio(0); } while (0)
; #define PG8_WAIT_V(n) asm volatile("s_waitcnt vmcnt(" #n ")" ::: "memory")
; #define PG8_WAIT_L(n) asm volatile("s_waitcnt lgkmcnt(" #n ")" ::: "memory")
; #define PG8_BAR __builtin_amdgcn_s_barrier()
; #define PG8_SCHED __builtin_amdgcn_sched_barrier(0)
; template <class Epi, bool ALIGN_EPI>
; __device__ __forceinline__ void gemm_phase(LAS unsigned char* lds, const Gemm g, const StaticOrder& S, const Epi& E) {
;     ...
;             PG8_LDB(B0, 1, 0); PG8_LDB(B1, 1, 1); PG8_SCHED; PG8_LDA(At, 1, 0); PG8_STAGE(PG8_SA(0, 1), a2 + hstepA, voffA);
;             PG8_WAIT_V(8); PG8_WAIT_L(0); PG8_BAR; PG8_MMA(0, 0, At, B0); PG8_MMA(0, 1, At, B1); PG8_BAR; PG8_SCHED;
;             PG8_LDA(At, 1, 1); PG8_STAGE(PG8_SB(1, 0), b3, voffB); PG8_STAGE(PG8_SB(1, 1), b3 + hstepB, voffB); PG8_STAGE(PG8_SA(1, 0), a3, voffA);
;             PG8_WAIT_V(8); PG8_WAIT_L(0); PG8_BAR; PG8_MMA(1, 0, At, B0); PG8_MMA(1, 1, At, B1); PG8_BAR; PG8_SCHED;
;         }
	v_add_u32_e32 v142, 0x18000, v245
	v_add_u32_e32 v158, 0x1c000, v245
	ds_read_b128 v[130:133], v142
	ds_read_b128 v[134:137], v142 offset:1024
	ds_read_b128 v[138:141], v142 offset:2048
	ds_read_b128 v[142:145], v142 offset:3072
	ds_read_b128 v[146:149], v158
	ds_read_b128 v[150:153], v158 offset:1024
	ds_read_b128 v[154:157], v158 offset:2048
	ds_read_b128 v[158:161], v158 offset:3072
	ds_read_b128 v[162:165], v246 offset:32768
	ds_read_b128 v[166:169], v246 offset:33792
	ds_read_b128 v[170:173], v246 offset:34816
	ds_read_b128 v[174:177], v246 offset:35840
	ds_read_b128 v[178:181], v246 offset:36864
	ds_read_b128 v[182:185], v246 offset:37888
	ds_read_b128 v[186:189], v246 offset:38912
	ds_read_b128 v[190:193], v246 offset:39936
	s_add_u32 s56, s56, s38
	s_addc_u32 s57, s57, 0
	s_mov_b32 m0, s31
	s_nop 0
	global_load_lds_dwordx4 v0, s[56:57]
	s_nop 0
	s_mov_b32 m0, s53
	s_nop 0
	global_load_lds_dwordx4 v206, s[56:57]
	s_waitcnt vmcnt(8)
	s_waitcnt lgkmcnt(0)
	s_barrier
	s_setprio 1
	s_waitcnt lgkmcnt(0)
	v_mfma_f32_16x16x32_bf16 v[126:129], v[130:133], v[162:165], v[126:129]
	v_mfma_f32_16x16x32_bf16 v[126:129], v[134:137], v[166:169], v[126:129]
	v_mfma_f32_16x16x32_bf16 v[122:125], v[138:141], v[162:165], v[122:125]
	v_mfma_f32_16x16x32_bf16 v[122:125], v[142:145], v[166:169], v[122:125]
	v_mfma_f32_16x16x32_bf16 v[118:121], v[146:149], v[162:165], v[118:121]
	v_mfma_f32_16x16x32_bf16 v[118:121], v[150:153], v[166:169], v[118:121]
	v_mfma_f32_16x16x32_bf16 v[114:117], v[154:157], v[162:165], v[114:117]
	v_mfma_f32_16x16x32_bf16 v[114:117], v[158:161], v[166:169], v[114:117]
	v_mfma_f32_16x16x32_bf16 v[98:101], v[154:157], v[170:173], v[98:101]
	v_mfma_f32_16x16x32_bf16 v[98:101], v[158:161], v[174:177], v[98:101]
	v_mfma_f32_16x16x32_bf16 v[102:105], v[146:149], v[170:173], v[102:105]
	v_mfma_f32_16x16x32_bf16 v[102:105], v[150:153], v[174:177], v[102:105]
	v_mfma_f32_16x16x32_bf16 v[106:109], v[138:141], v[170:173], v[106:109]
	v_mfma_f32_16x16x32_bf16 v[106:109], v[142:145], v[174:177], v[106:109]
	v_mfma_f32_16x16x32_bf16 v[110:113], v[130:133], v[170:173], v[110:113]
	v_mfma_f32_16x16x32_bf16 v[110:113], v[134:137], v[174:177], v[110:113]
	v_mfma_f32_16x16x32_bf16 v[94:97], v[130:133], v[178:181], v[94:97]
	v_mfma_f32_16x16x32_bf16 v[94:97], v[134:137], v[182:185], v[94:97]
	v_mfma_f32_16x16x32_bf16 v[90:93], v[138:141], v[178:181], v[90:93]
	v_mfma_f32_16x16x32_bf16 v[90:93], v[142:145], v[182:185], v[90:93]
	v_mfma_f32_16x16x32_bf16 v[86:89], v[146:149], v[178:181], v[86:89]
	v_mfma_f32_16x16x32_bf16 v[86:89], v[150:153], v[182:185], v[86:89]
	v_mfma_f32_16x16x32_bf16 v[82:85], v[154:157], v[178:181], v[82:85]
	v_mfma_f32_16x16x32_bf16 v[82:85], v[158:161], v[182:185], v[82:85]
	v_mfma_f32_16x16x32_bf16 v[66:69], v[154:157], v[186:189], v[66:69]
	v_mfma_f32_16x16x32_bf16 v[66:69], v[158:161], v[190:193], v[66:69]
	v_mfma_f32_16x16x32_bf16 v[70:73], v[146:149], v[186:189], v[70:73]
	v_mfma_f32_16x16x32_bf16 v[70:73], v[150:153], v[190:193], v[70:73]
	v_mfma_f32_16x16x32_bf16 v[74:77], v[138:141], v[186:189], v[74:77]
	v_mfma_f32_16x16x32_bf16 v[74:77], v[142:145], v[190:193], v[74:77]
	v_mfma_f32_16x16x32_bf16 v[78:81], v[130:133], v[186:189], v[78:81]
	v_mfma_f32_16x16x32_bf16 v[78:81], v[134:137], v[190:193], v[78:81]
	s_setprio 0
	s_barrier
	ds_read_b128 v[162:165], v246 offset:49152
	ds_read_b128 v[166:169], v246 offset:50176
	ds_read_b128 v[170:173], v246 offset:51200
	ds_read_b128 v[174:177], v246 offset:52224
	ds_read_b128 v[178:181], v246 offset:53248
	ds_read_b128 v[182:185], v246 offset:54272
	ds_read_b128 v[186:189], v246 offset:55296
	ds_read_b128 v[190:193], v246 offset:56320
	s_add_u32 s54, s54, 0x80
	s_addc_u32 s55, s55, 0
	s_mov_b32 m0, s85
	s_nop 0
	global_load_lds_dwordx4 v195, s[54:55]
	s_nop 0
	s_mov_b32 m0, s65
	s_nop 0
	global_load_lds_dwordx4 v207, s[54:55]
	s_add_u32 s54, s58, 0x80
	s_addc_u32 s55, s59, 0
	s_mov_b32 m0, s93
	s_nop 0
	global_load_lds_dwordx4 v195, s[54:55]
	s_nop 0
	s_mov_b32 m0, s28
	s_nop 0
	global_load_lds_dwordx4 v207, s[54:55]
	s_nop 0
	s_mov_b32 m0, s67
	s_nop 0
	global_load_lds_dwordx4 v0, s[48:49]
	s_nop 0
	s_mov_b32 m0, s92
	s_nop 0
	global_load_lds_dwordx4 v206, s[48:49]
	s_waitcnt vmcnt(8)
	s_waitcnt lgkmcnt(0)
	s_barrier
	s_setprio 1
	s_waitcnt lgkmcnt(0)
	v_mfma_f32_16x16x32_bf16 v[62:65], v[130:133], v[162:165], v[62:65]
	v_mfma_f32_16x16x32_bf16 v[62:65], v[134:137], v[166:169], v[62:65]
	v_mfma_f32_16x16x32_bf16 v[58:61], v[138:141], v[162:165], v[58:61]
	v_mfma_f32_16x16x32_bf16 v[58:61], v[142:145], v[166:169], v[58:61]
	v_mfma_f32_16x16x32_bf16 v[54:57], v[146:149], v[162:165], v[54:57]
	v_mfma_f32_16x16x32_bf16 v[54:57], v[150:153], v[166:169], v[54:57]
	v_mfma_f32_16x16x32_bf16 v[50:53], v[154:157], v[162:165], v[50:53]
	v_mfma_f32_16x16x32_bf16 v[50:53], v[158:161], v[166:169], v[50:53]
	v_mfma_f32_16x16x32_bf16 v[34:37], v[154:157], v[170:173], v[34:37]
	v_mfma_f32_16x16x32_bf16 v[34:37], v[158:161], v[174:177], v[34:37]
	v_mfma_f32_16x16x32_bf16 v[38:41], v[146:149], v[170:173], v[38:41]
	v_mfma_f32_16x16x32_bf16 v[38:41], v[150:153], v[174:177], v[38:41]
	v_mfma_f32_16x16x32_bf16 v[42:45], v[138:141], v[170:173], v[42:45]
	v_mfma_f32_16x16x32_bf16 v[42:45], v[142:145], v[174:177], v[42:45]
	v_mfma_f32_16x16x32_bf16 v[46:49], v[130:133], v[170:173], v[46:49]
	v_mfma_f32_16x16x32_bf16 v[46:49], v[134:137], v[174:177], v[46:49]
	v_mfma_f32_16x16x32_bf16 v[30:33], v[130:133], v[178:181], v[30:33]
	v_mfma_f32_16x16x32_bf16 v[30:33], v[134:137], v[182:185], v[30:33]
	v_mfma_f32_16x16x32_bf16 v[26:29], v[138:141], v[178:181], v[26:29]
	v_mfma_f32_16x16x32_bf16 v[26:29], v[142:145], v[182:185], v[26:29]
	v_mfma_f32_16x16x32_bf16 v[22:25], v[146:149], v[178:181], v[22:25]
	v_mfma_f32_16x16x32_bf16 v[22:25], v[150:153], v[182:185], v[22:25]
	v_mfma_f32_16x16x32_bf16 v[18:21], v[154:157], v[178:181], v[18:21]
	v_mfma_f32_16x16x32_bf16 v[18:21], v[158:161], v[182:185], v[18:21]
	v_mfma_f32_16x16x32_bf16 v[2:5], v[154:157], v[186:189], v[2:5]
	v_mfma_f32_16x16x32_bf16 v[2:5], v[158:161], v[190:193], v[2:5]
	v_mfma_f32_16x16x32_bf16 v[6:9], v[146:149], v[186:189], v[6:9]
	v_mfma_f32_16x16x32_bf16 v[6:9], v[150:153], v[190:193], v[6:9]
	v_mfma_f32_16x16x32_bf16 v[10:13], v[138:141], v[186:189], v[10:13]
	v_mfma_f32_16x16x32_bf16 v[10:13], v[142:145], v[190:193], v[10:13]
	v_mfma_f32_16x16x32_bf16 v[14:17], v[130:133], v[186:189], v[14:17]
	v_mfma_f32_16x16x32_bf16 v[14:17], v[134:137], v[190:193], v[14:17]
	s_setprio 0
	s_barrier
	s_add_u32 s4, s4, 0x100
	s_addc_u32 s5, s5, 0
	s_add_u32 s15, s15, 0x100
	s_addc_u32 s42, s42, 0
	s_cmp_ge_u32 s44, s36
	s_mov_b32 s43, s44

; #define PG8_STAGE(bufoff, gbase, voff) do { _Pragma("unroll") for (int _i = 0; _i < 2; ++_i) { \
;         const unsigned _m0 = ldsb + (unsigned)((bufoff) + _i * 8192); const char* _gb = (const char*)(gbase); \
;         asm volatile("s_mov_b32 m0, %0\n\ts_nop 0\n\tglobal_load_lds_dwordx4 %1, %2" :: "s"(_m0), "v"((voff)[_i]), "s"(_gb) : "m0", "memory"); } } while (0)
; #define PG8_LDA(dst, b, h) do { _Pragma("unroll") for (int m = 0; m < 4; ++m) _Pragma("unroll") for (int k = 0; k < 2; ++k) dst[m][k] = *(const LAS bf16x8*)(lds + PG8_SA(b, h) + aoff + m * 2048 + k * 1024); } while (0)
; #define PG8_LDB(dst, b, h) do { _Pragma("unroll") for (int n = 0; n < 2; ++n) _Pragma("unroll") for (int k = 0; k < 2; ++k) dst[n][k] = *(const LAS bf16x8*)(lds + PG8_SB(b, h) + boff + n * 2048 + k * 1024); } while (0)
; #define PG8_MMA(ai, bj, At, Bt) do { __builtin_amdgcn_s_setprio(1); _Pragma("unroll") for (int m = 0; m < 4; ++m) _Pragma("unroll") for (int n = 0; n < 2; ++n) _Pragma("unroll") for (int k = 0; k < 2; ++k) \
;         acc[ai][bj][m][n] = __builtin_amdgcn_mfma_f32_16x16x32_bf16(Bt[n][k], At[m][k], acc[ai][bj][m][n], 0, 0, 0); __builtin_amdgcn_s_setprio(0); } while (0)
; #define PG8_WAIT_V(n) asm volatile("s_waitcnt vmcnt(" #n ")" ::: "memory")
; #define PG8_WAIT_L(n) asm volatile("s_waitcnt lgkmcnt(" #n ")" ::: "memory")
; template <class Epi, bool ALIGN_EPI>
; __device__ __forceinline__ void gemm_phase(LAS unsigned char* lds, const Gemm g, const StaticOrder& S, const Epi& E) {
;     ...
;         for (int t = 0; t < nt; t += 2) {
;             const bool last = (t == nt - 2);
;             const char* a1 = cA + (size_t)(t + 1) * kstep;
;             const char* a2 = last ? nA : cA + (size_t)(t + 2) * kstep; const char* b2 = last ? nB : cB + (size_t)(t + 2) * kstep;
;             const char* a3 = a2 + kstep; const char* b3 = b2 + kstep;
;             PG8_LDB(B0, 0, 0); PG8_LDB(B1, 0, 1); PG8_SCHED; PG8_LDA(At, 0, 0); PG8_STAGE(PG8_SA(1, 1), a1 + hstepA, voffA);
;             PG8_WAIT_V(8); PG8_WAIT_L(0); PG8_BAR; PG8_MMA(0, 0, At, B0); PG8_MMA(0, 1, At, B1); PG8_BAR; PG8_SCHED;
;             PG8_LDA(At, 0, 1); PG8_STAGE(PG8_SB(0, 0), b2, voffB); PG8_STAGE(PG8_SB(0, 1), b2 + hstepB, voffB); PG8_STAGE(PG8_SA(0, 0), a2, voffA);
;             PG8_WAIT_V(8); PG8_WAIT_L(0); PG8_BAR; PG8_MMA(1, 0, At, B0); PG8_MMA(1, 1, At, B1); PG8_BAR; PG8_SCHED;
.LBB0_270:
	s_add_u32 s4, s56, 0x100
	s_addc_u32 s5, s57, 0
	s_add_u32 s0, s58, 0x40080
	s_addc_u32 s1, s59, 0
	s_mov_b32 s44, 0
	v_add_u32_e32 v0, 0x10000, v179
	ds_read_b128 v[130:133], v0
	ds_read_b128 v[134:137], v0 offset:1024
	ds_read_b128 v[138:141], v0 offset:2048
	ds_read_b128 v[142:145], v0 offset:3072
	v_add_u32_e32 v0, 0x14000, v179
	ds_read_b128 v[146:149], v0
	ds_read_b128 v[150:153], v0 offset:1024
	ds_read_b128 v[154:157], v0 offset:2048
	ds_read_b128 v[158:161], v0 offset:3072
	s_add_i32 s55, s44, 2
	s_add_u32 s45, s0, 0xfffc0080
	s_addc_u32 s56, s1, -1
	s_cmp_eq_u32 s68, s44
	s_cselect_b32 s60, s96, s45
	s_cselect_b32 s61, s97, s56
	s_cselect_b32 s58, s48, s4
	s_cselect_b32 s59, s49, s5
	s_add_u32 s56, s60, 0x80
	s_addc_u32 s57, s61, 0
	ds_read_b128 v[182:185], v180
	ds_read_b128 v[186:189], v180 offset:1024
	ds_read_b128 v[190:193], v180 offset:2048
	ds_read_b128 v[202:205], v180 offset:3072
	ds_read_b128 v[206:209], v180 offset:4096
	ds_read_b128 v[210:213], v180 offset:5120
	ds_read_b128 v[214:217], v180 offset:6144
	ds_read_b128 v[240:243], v180 offset:7168
	s_mov_b32 m0, s41
	s_nop 0
	global_load_lds_dwordx4 v165, s[0:1]
	s_nop 0
	s_mov_b32 m0, s30
	s_nop 0
	global_load_lds_dwordx4 v171, s[0:1]
	s_waitcnt vmcnt(8)
	s_waitcnt lgkmcnt(0)
	s_barrier
	s_setprio 1
	s_waitcnt lgkmcnt(0)
	v_mfma_f32_16x16x32_bf16 v[126:129], v[130:133], v[182:185], 0
	v_mfma_f32_16x16x32_bf16 v[126:129], v[134:137], v[186:189], v[126:129]
	v_mfma_f32_16x16x32_bf16 v[122:125], v[138:141], v[182:185], 0
	v_mfma_f32_16x16x32_bf16 v[122:125], v[142:145], v[186:189], v[122:125]
	v_mfma_f32_16x16x32_bf16 v[118:121], v[146:149], v[182:185], 0
	v_mfma_f32_16x16x32_bf16 v[118:121], v[150:153], v[186:189], v[118:121]
	v_mfma_f32_16x16x32_bf16 v[110:113], v[154:157], v[182:185], 0
	v_mfma_f32_16x16x32_bf16 v[110:113], v[158:161], v[186:189], v[110:113]
	v_mfma_f32_16x16x32_bf16 v[94:97], v[154:157], v[190:193], 0
	v_mfma_f32_16x16x32_bf16 v[94:97], v[158:161], v[202:205], v[94:97]
	v_mfma_f32_16x16x32_bf16 v[102:105], v[146:149], v[190:193], 0
	v_mfma_f32_16x16x32_bf16 v[102:105], v[150:153], v[202:205], v[102:105]
	v_mfma_f32_16x16x32_bf16 v[106:109], v[138:141], v[190:193], 0
	v_mfma_f32_16x16x32_bf16 v[106:109], v[142:145], v[202:205], v[106:109]
	v_mfma_f32_16x16x32_bf16 v[114:117], v[130:133], v[190:193], 0
	v_mfma_f32_16x16x32_bf16 v[114:117], v[134:137], v[202:205], v[114:117]
	v_mfma_f32_16x16x32_bf16 v[98:101], v[130:133], v[206:209], 0
	v_mfma_f32_16x16x32_bf16 v[98:101], v[134:137], v[210:213], v[98:101]
	v_mfma_f32_16x16x32_bf16 v[90:93], v[138:141], v[206:209], 0
	v_mfma_f32_16x16x32_bf16 v[90:93], v[142:145], v[210:213], v[90:93]
	v_mfma_f32_16x16x32_bf16 v[86:89], v[146:149], v[206:209], 0
	v_mfma_f32_16x16x32_bf16 v[86:89], v[150:153], v[210:213], v[86:89]
	v_mfma_f32_16x16x32_bf16 v[78:81], v[154:157], v[206:209], 0
	v_mfma_f32_16x16x32_bf16 v[78:81], v[158:161], v[210:213], v[78:81]
	v_mfma_f32_16x16x32_bf16 v[66:69], v[154:157], v[214:217], 0
	v_mfma_f32_16x16x32_bf16 v[66:69], v[158:161], v[240:243], v[66:69]
	v_mfma_f32_16x16x32_bf16 v[70:73], v[146:149], v[214:217], 0
	v_mfma_f32_16x16x32_bf16 v[70:73], v[150:153], v[240:243], v[70:73]
	v_mfma_f32_16x16x32_bf16 v[74:77], v[138:141], v[214:217], 0
	v_mfma_f32_16x16x32_bf16 v[74:77], v[142:145], v[240:243], v[74:77]
	v_mfma_f32_16x16x32_bf16 v[82:85], v[130:133], v[214:217], 0
	v_mfma_f32_16x16x32_bf16 v[82:85], v[134:137], v[240:243], v[82:85]
	s_setprio 0
	s_barrier
	ds_read_b128 v[182:185], v180 offset:16384
	ds_read_b128 v[186:189], v180 offset:17408
	ds_read_b128 v[190:193], v180 offset:18432
	ds_read_b128 v[202:205], v180 offset:19456
	ds_read_b128 v[206:209], v180 offset:20480
	ds_read_b128 v[210:213], v180 offset:21504
	ds_read_b128 v[214:217], v180 offset:22528
	ds_read_b128 v[240:243], v180 offset:23552
	s_mov_b32 m0, s42
	s_nop 0
	global_load_lds_dwordx4 v167, s[58:59]
	s_add_u32 s44, s58, s14
	s_mov_b32 m0, s43
	s_nop 0
	global_load_lds_dwordx4 v175, s[58:59]
	s_addc_u32 s45, s59, 0
	s_mov_b32 m0, s46
	s_nop 0
	global_load_lds_dwordx4 v167, s[44:45]
	s_nop 0
	s_mov_b32 m0, s50
	s_nop 0
	global_load_lds_dwordx4 v175, s[44:45]
	s_nop 0
	s_mov_b32 m0, s17
	s_nop 0
	global_load_lds_dwordx4 v165, s[60:61]
	s_nop 0
	s_mov_b32 m0, s53
	s_nop 0
	global_load_lds_dwordx4 v171, s[60:61]
	s_waitcnt vmcnt(8)
	s_waitcnt lgkmcnt(0)
	s_barrier
	s_setprio 1
	s_waitcnt lgkmcnt(0)
	v_mfma_f32_16x16x32_bf16 v[62:65], v[130:133], v[182:185], 0
	v_mfma_f32_16x16x32_bf16 v[62:65], v[134:137], v[186:189], v[62:65]
	v_mfma_f32_16x16x32_bf16 v[58:61], v[138:141], v[182:185], 0
	v_mfma_f32_16x16x32_bf16 v[58:61], v[142:145], v[186:189], v[58:61]
	v_mfma_f32_16x16x32_bf16 v[54:57], v[146:149], v[182:185], 0
	v_mfma_f32_16x16x32_bf16 v[54:57], v[150:153], v[186:189], v[54:57]
	v_mfma_f32_16x16x32_bf16 v[50:53], v[154:157], v[182:185], 0
	v_mfma_f32_16x16x32_bf16 v[50:53], v[158:161], v[186:189], v[50:53]
	v_mfma_f32_16x16x32_bf16 v[30:33], v[154:157], v[190:193], 0
	v_mfma_f32_16x16x32_bf16 v[30:33], v[158:161], v[202:205], v[30:33]
	v_mfma_f32_16x16x32_bf16 v[38:41], v[146:149], v[190:193], 0
	v_mfma_f32_16x16x32_bf16 v[38:41], v[150:153], v[202:205], v[38:41]
	v_mfma_f32_16x16x32_bf16 v[42:45], v[138:141], v[190:193], 0
	v_mfma_f32_16x16x32_bf16 v[42:45], v[142:145], v[202:205], v[42:45]
	v_mfma_f32_16x16x32_bf16 v[46:49], v[130:133], v[190:193], 0
	v_mfma_f32_16x16x32_bf16 v[46:49], v[134:137], v[202:205], v[46:49]
	v_mfma_f32_16x16x32_bf16 v[34:37], v[130:133], v[206:209], 0
	v_mfma_f32_16x16x32_bf16 v[34:37], v[134:137], v[210:213], v[34:37]
	v_mfma_f32_16x16x32_bf16 v[26:29], v[138:141], v[206:209], 0
	v_mfma_f32_16x16x32_bf16 v[26:29], v[142:145], v[210:213], v[26:29]
	v_mfma_f32_16x16x32_bf16 v[22:25], v[146:149], v[206:209], 0
	v_mfma_f32_16x16x32_bf16 v[22:25], v[150:153], v[210:213], v[22:25]
	v_mfma_f32_16x16x32_bf16 v[14:17], v[154:157], v[206:209], 0
	v_mfma_f32_16x16x32_bf16 v[14:17], v[158:161], v[210:213], v[14:17]
	v_mfma_f32_16x16x32_bf16 v[2:5], v[154:157], v[214:217], 0
	v_mfma_f32_16x16x32_bf16 v[2:5], v[158:161], v[240:243], v[2:5]
	v_mfma_f32_16x16x32_bf16 v[6:9], v[146:149], v[214:217], 0
	v_mfma_f32_16x16x32_bf16 v[6:9], v[150:153], v[240:243], v[6:9]
	v_mfma_f32_16x16x32_bf16 v[10:13], v[138:141], v[214:217], 0
	v_mfma_f32_16x16x32_bf16 v[10:13], v[142:145], v[240:243], v[10:13]
	v_mfma_f32_16x16x32_bf16 v[18:21], v[130:133], v[214:217], 0
	v_mfma_f32_16x16x32_bf16 v[18:21], v[134:137], v[240:243], v[18:21]
	s_setprio 0
	s_barrier
; #define PG8_STAGE(bufoff, gbase, voff) do { _Pragma("unroll") for (int _i = 0; _i < 2; ++_i) { \
;         const unsigned _m0 = ldsb + (unsigned)((bufoff) + _i * 8192); const char* _gb = (const char*)(gbase); \
;         asm volatile("s_mov_b32 m0, %0\n\ts_nop 0\n\tglobal_load_lds_dwordx4 %1, %2" :: "s"(_m0), "v"((voff)[_i]), "s"(_gb) : "m0", "memory"); } } while (0)
; #define PG8_LDA(dst, b, h) do { _Pragma("unroll") for (int m = 0; m < 4; ++m) _Pragma("unroll") for (int k = 0; k < 2; ++k) dst[m][k] = *(const LAS bf16x8*)(lds + PG8_SA(b, h) + aoff + m * 2048 + k * 1024); } while (0)
; #define PG8_LDB(dst, b, h) do { _Pragma("unroll") for (int n = 0; n < 2; ++n) _Pragma("unroll") for (int k = 0; k < 2; ++k) dst[n][k] = *(const LAS bf16x8*)(lds + PG8_SB(b, h) + boff + n * 2048 + k * 1024); } while (0)
; #define PG8_MMA(ai, bj, At, Bt) do { __builtin_amdgcn_s_setprio(1); _Pragma("unroll") for (int m = 0; m < 4; ++m) _Pragma("unroll") for (int n = 0; n < 2; ++n) _Pragma("unroll") for (int k = 0; k < 2; ++k) \
;         acc[ai][bj][m][n] = __builtin_amdgcn_mfma_f32_16x16x32_bf16(Bt[n][k], At[m][k], acc[ai][bj][m][n], 0, 0, 0); __builtin_amdgcn_s_setprio(0); } while (0)
; #define PG8_WAIT_V(n) asm volatile("s_waitcnt vmcnt(" #n ")" ::: "memory")
; #define PG8_WAIT_L(n) asm volatile("s_waitcnt lgkmcnt(" #n ")" ::: "memory")
; #define PG8_BAR __builtin_amdgcn_s_barrier()
; #define PG8_SCHED __builtin_amdgcn_sched_barrier(0)
; template <class Epi, bool ALIGN_EPI>
; __device__ __forceinline__ void gemm_phase(LAS unsigned char* lds, const Gemm g, const StaticOrder& S, const Epi& E) {
;     ...
;             PG8_LDB(B0, 1, 0); PG8_LDB(B1, 1, 1); PG8_SCHED; PG8_LDA(At, 1, 0); PG8_STAGE(PG8_SA(0, 1), a2 + hstepA, voffA);
;             PG8_WAIT_V(8); PG8_WAIT_L(0); PG8_BAR; PG8_MMA(0, 0, At, B0); PG8_MMA(0, 1, At, B1); PG8_BAR; PG8_SCHED;
;             PG8_LDA(At, 1, 1); PG8_STAGE(PG8_SB(1, 0), b3, voffB); PG8_STAGE(PG8_SB(1, 1), b3 + hstepB, voffB); PG8_STAGE(PG8_SA(1, 0), a3, voffA);
;             PG8_WAIT_V(8); PG8_WAIT_L(0); PG8_BAR; PG8_MMA(1, 0, At, B0); PG8_MMA(1, 1, At, B1); PG8_BAR; PG8_SCHED;
;         }
	v_add_u32_e32 v0, 0x18000, v179
	ds_read_b128 v[130:133], v0
	ds_read_b128 v[134:137], v0 offset:1024
	ds_read_b128 v[138:141], v0 offset:2048
	ds_read_b128 v[142:145], v0 offset:3072
	v_add_u32_e32 v0, 0x1c000, v179
	ds_read_b128 v[146:149], v0
	ds_read_b128 v[150:153], v0 offset:1024
	ds_read_b128 v[154:157], v0 offset:2048
	ds_read_b128 v[158:161], v0 offset:3072
	ds_read_b128 v[182:185], v180 offset:32768
	ds_read_b128 v[186:189], v180 offset:33792
	ds_read_b128 v[190:193], v180 offset:34816
	ds_read_b128 v[202:205], v180 offset:35840
	ds_read_b128 v[206:209], v180 offset:36864
	ds_read_b128 v[210:213], v180 offset:37888
	ds_read_b128 v[214:217], v180 offset:38912
	ds_read_b128 v[240:243], v180 offset:39936
	s_add_u32 s60, s60, 0x40000
	s_addc_u32 s61, s61, 0
	s_mov_b32 m0, s65
	s_nop 0
	global_load_lds_dwordx4 v165, s[60:61]
	s_nop 0
	s_mov_b32 m0, s67
	s_nop 0
	global_load_lds_dwordx4 v171, s[60:61]
	s_waitcnt vmcnt(8)
	s_waitcnt lgkmcnt(0)
	s_barrier
	s_setprio 1
	s_waitcnt lgkmcnt(0)
	v_mfma_f32_16x16x32_bf16 v[126:129], v[130:133], v[182:185], v[126:129]
	v_mfma_f32_16x16x32_bf16 v[126:129], v[134:137], v[186:189], v[126:129]
	v_mfma_f32_16x16x32_bf16 v[122:125], v[138:141], v[182:185], v[122:125]
	v_mfma_f32_16x16x32_bf16 v[122:125], v[142:145], v[186:189], v[122:125]
	v_mfma_f32_16x16x32_bf16 v[118:121], v[146:149], v[182:185], v[118:121]
	v_mfma_f32_16x16x32_bf16 v[118:121], v[150:153], v[186:189], v[118:121]
	v_mfma_f32_16x16x32_bf16 v[110:113], v[154:157], v[182:185], v[110:113]
	v_mfma_f32_16x16x32_bf16 v[110:113], v[158:161], v[186:189], v[110:113]
	v_mfma_f32_16x16x32_bf16 v[94:97], v[154:157], v[190:193], v[94:97]
	v_mfma_f32_16x16x32_bf16 v[94:97], v[158:161], v[202:205], v[94:97]
	v_mfma_f32_16x16x32_bf16 v[102:105], v[146:149], v[190:193], v[102:105]
	v_mfma_f32_16x16x32_bf16 v[102:105], v[150:153], v[202:205], v[102:105]
	v_mfma_f32_16x16x32_bf16 v[106:109], v[138:141], v[190:193], v[106:109]
	v_mfma_f32_16x16x32_bf16 v[106:109], v[142:145], v[202:205], v[106:109]
	v_mfma_f32_16x16x32_bf16 v[114:117], v[130:133], v[190:193], v[114:117]
	v_mfma_f32_16x16x32_bf16 v[114:117], v[134:137], v[202:205], v[114:117]
	v_mfma_f32_16x16x32_bf16 v[98:101], v[130:133], v[206:209], v[98:101]
	v_mfma_f32_16x16x32_bf16 v[98:101], v[134:137], v[210:213], v[98:101]
	v_mfma_f32_16x16x32_bf16 v[90:93], v[138:141], v[206:209], v[90:93]
	v_mfma_f32_16x16x32_bf16 v[90:93], v[142:145], v[210:213], v[90:93]
	v_mfma_f32_16x16x32_bf16 v[86:89], v[146:149], v[206:209], v[86:89]
	v_mfma_f32_16x16x32_bf16 v[86:89], v[150:153], v[210:213], v[86:89]
	v_mfma_f32_16x16x32_bf16 v[78:81], v[154:157], v[206:209], v[78:81]
	v_mfma_f32_16x16x32_bf16 v[78:81], v[158:161], v[210:213], v[78:81]
	v_mfma_f32_16x16x32_bf16 v[66:69], v[154:157], v[214:217], v[66:69]
	v_mfma_f32_16x16x32_bf16 v[66:69], v[158:161], v[240:243], v[66:69]
	v_mfma_f32_16x16x32_bf16 v[70:73], v[146:149], v[214:217], v[70:73]
	v_mfma_f32_16x16x32_bf16 v[70:73], v[150:153], v[240:243], v[70:73]
	v_mfma_f32_16x16x32_bf16 v[74:77], v[138:141], v[214:217], v[74:77]
	v_mfma_f32_16x16x32_bf16 v[74:77], v[142:145], v[240:243], v[74:77]
	v_mfma_f32_16x16x32_bf16 v[82:85], v[130:133], v[214:217], v[82:85]
	v_mfma_f32_16x16x32_bf16 v[82:85], v[134:137], v[240:243], v[82:85]
	s_setprio 0
	s_barrier
	ds_read_b128 v[182:185], v180 offset:49152
	ds_read_b128 v[186:189], v180 offset:50176
	ds_read_b128 v[190:193], v180 offset:51200
	ds_read_b128 v[202:205], v180 offset:52224
	ds_read_b128 v[206:209], v180 offset:53248
	ds_read_b128 v[210:213], v180 offset:54272
	ds_read_b128 v[214:217], v180 offset:55296
	ds_read_b128 v[240:243], v180 offset:56320
	s_add_u32 s58, s58, 0x80
	s_addc_u32 s59, s59, 0
	s_mov_b32 m0, s89
	s_nop 0
	global_load_lds_dwordx4 v167, s[58:59]
	s_add_u32 s44, s44, 0x80
	s_mov_b32 m0, s95
	s_nop 0
	global_load_lds_dwordx4 v175, s[58:59]
	s_addc_u32 s45, s45, 0
	s_mov_b32 m0, s26
	s_nop 0
	global_load_lds_dwordx4 v167, s[44:45]
	s_nop 0
	s_mov_b32 m0, s27
	s_nop 0
	global_load_lds_dwordx4 v175, s[44:45]
	s_nop 0
	s_mov_b32 m0, s36
	s_nop 0
	global_load_lds_dwordx4 v165, s[56:57]
	s_nop 0
	s_mov_b32 m0, s37
	s_nop 0
	global_load_lds_dwordx4 v171, s[56:57]
	s_waitcnt vmcnt(8)
	s_waitcnt lgkmcnt(0)
	s_barrier
	s_setprio 1
	s_waitcnt lgkmcnt(0)
	v_mfma_f32_16x16x32_bf16 v[62:65], v[130:133], v[182:185], v[62:65]
	v_mfma_f32_16x16x32_bf16 v[62:65], v[134:137], v[186:189], v[62:65]
	v_mfma_f32_16x16x32_bf16 v[58:61], v[138:141], v[182:185], v[58:61]
	v_mfma_f32_16x16x32_bf16 v[58:61], v[142:145], v[186:189], v[58:61]
	v_mfma_f32_16x16x32_bf16 v[54:57], v[146:149], v[182:185], v[54:57]
	v_mfma_f32_16x16x32_bf16 v[54:57], v[150:153], v[186:189], v[54:57]
	v_mfma_f32_16x16x32_bf16 v[50:53], v[154:157], v[182:185], v[50:53]
	v_mfma_f32_16x16x32_bf16 v[50:53], v[158:161], v[186:189], v[50:53]
	v_mfma_f32_16x16x32_bf16 v[30:33], v[154:157], v[190:193], v[30:33]
	v_mfma_f32_16x16x32_bf16 v[30:33], v[158:161], v[202:205], v[30:33]
	v_mfma_f32_16x16x32_bf16 v[38:41], v[146:149], v[190:193], v[38:41]
	v_mfma_f32_16x16x32_bf16 v[38:41], v[150:153], v[202:205], v[38:41]
	v_mfma_f32_16x16x32_bf16 v[42:45], v[138:141], v[190:193], v[42:45]
	v_mfma_f32_16x16x32_bf16 v[42:45], v[142:145], v[202:205], v[42:45]
	v_mfma_f32_16x16x32_bf16 v[46:49], v[130:133], v[190:193], v[46:49]
	v_mfma_f32_16x16x32_bf16 v[46:49], v[134:137], v[202:205], v[46:49]
	v_mfma_f32_16x16x32_bf16 v[34:37], v[130:133], v[206:209], v[34:37]
	v_mfma_f32_16x16x32_bf16 v[34:37], v[134:137], v[210:213], v[34:37]
	v_mfma_f32_16x16x32_bf16 v[26:29], v[138:141], v[206:209], v[26:29]
	v_mfma_f32_16x16x32_bf16 v[26:29], v[142:145], v[210:213], v[26:29]
	v_mfma_f32_16x16x32_bf16 v[22:25], v[146:149], v[206:209], v[22:25]
	v_mfma_f32_16x16x32_bf16 v[22:25], v[150:153], v[210:213], v[22:25]
	v_mfma_f32_16x16x32_bf16 v[14:17], v[154:157], v[206:209], v[14:17]
	v_mfma_f32_16x16x32_bf16 v[14:17], v[158:161], v[210:213], v[14:17]
	v_mfma_f32_16x16x32_bf16 v[2:5], v[154:157], v[214:217], v[2:5]
	v_mfma_f32_16x16x32_bf16 v[2:5], v[158:161], v[240:243], v[2:5]
	v_mfma_f32_16x16x32_bf16 v[6:9], v[146:149], v[214:217], v[6:9]
	v_mfma_f32_16x16x32_bf16 v[6:9], v[150:153], v[240:243], v[6:9]
	v_mfma_f32_16x16x32_bf16 v[10:13], v[138:141], v[214:217], v[10:13]
	v_mfma_f32_16x16x32_bf16 v[10:13], v[142:145], v[240:243], v[10:13]
	v_mfma_f32_16x16x32_bf16 v[18:21], v[130:133], v[214:217], v[18:21]
	v_mfma_f32_16x16x32_bf16 v[18:21], v[134:137], v[240:243], v[18:21]
	s_setprio 0
	s_barrier
	s_add_u32 s4, s4, 0x100
	s_addc_u32 s5, s5, 0
	s_add_u32 s0, s0, 0x100
	s_addc_u32 s1, s1, 0
	s_cmp_ge_u32 s55, s31
	s_mov_b32 s44, s55

; #define PG8_STAGE(bufoff, gbase, voff) do { _Pragma("unroll") for (int _i = 0; _i < 2; ++_i) { \
;         const unsigned _m0 = ldsb + (unsigned)((bufoff) + _i * 8192); const char* _gb = (const char*)(gbase); \
;         asm volatile("s_mov_b32 m0, %0\n\ts_nop 0\n\tglobal_load_lds_dwordx4 %1, %2" :: "s"(_m0), "v"((voff)[_i]), "s"(_gb) : "m0", "memory"); } } while (0)
; #define PG8_LDA(dst, b, h) do { _Pragma("unroll") for (int m = 0; m < 4; ++m) _Pragma("unroll") for (int k = 0; k < 2; ++k) dst[m][k] = *(const LAS bf16x8*)(lds + PG8_SA(b, h) + aoff + m * 2048 + k * 1024); } while (0)
; #define PG8_LDB(dst, b, h) do { _Pragma("unroll") for (int n = 0; n < 2; ++n) _Pragma("unroll") for (int k = 0; k < 2; ++k) dst[n][k] = *(const LAS bf16x8*)(lds + PG8_SB(b, h) + boff + n * 2048 + k * 1024); } while (0)
; #define PG8_MMA(ai, bj, At, Bt) do { __builtin_amdgcn_s_setprio(1); _Pragma("unroll") for (int m = 0; m < 4; ++m) _Pragma("unroll") for (int n = 0; n < 2; ++n) _Pragma("unroll") for (int k = 0; k < 2; ++k) \
;         acc[ai][bj][m][n] = __builtin_amdgcn_mfma_f32_16x16x32_bf16(Bt[n][k], At[m][k], acc[ai][bj][m][n], 0, 0, 0); __builtin_amdgcn_s_setprio(0); } while (0)
; #define PG8_WAIT_V(n) asm volatile("s_waitcnt vmcnt(" #n ")" ::: "memory")
; #define PG8_WAIT_L(n) asm volatile("s_waitcnt lgkmcnt(" #n ")" ::: "memory")
; template <class Epi, bool ALIGN_EPI>
; __device__ __forceinline__ void gemm_phase(LAS unsigned char* lds, const Gemm g, const StaticOrder& S, const Epi& E) {
;     ...
;         for (int t = 0; t < nt; t += 2) {
;             const bool last = (t == nt - 2);
;             const char* a1 = cA + (size_t)(t + 1) * kstep;
;             const char* a2 = last ? nA : cA + (size_t)(t + 2) * kstep; const char* b2 = last ? nB : cB + (size_t)(t + 2) * kstep;
;             const char* a3 = a2 + kstep; const char* b3 = b2 + kstep;
;             PG8_LDB(B0, 0, 0); PG8_LDB(B1, 0, 1); PG8_SCHED; PG8_LDA(At, 0, 0); PG8_STAGE(PG8_SA(1, 1), a1 + hstepA, voffA);
;             PG8_WAIT_V(8); PG8_WAIT_L(0); PG8_BAR; PG8_MMA(0, 0, At, B0); PG8_MMA(0, 1, At, B1); PG8_BAR; PG8_SCHED;
;             PG8_LDA(At, 0, 1); PG8_STAGE(PG8_SB(0, 0), b2, voffB); PG8_STAGE(PG8_SB(0, 1), b2 + hstepB, voffB); PG8_STAGE(PG8_SA(0, 0), a2, voffA);
;             PG8_WAIT_V(8); PG8_WAIT_L(0); PG8_BAR; PG8_MMA(1, 0, At, B0); PG8_MMA(1, 1, At, B1); PG8_BAR; PG8_SCHED;
.LBB0_305:
	s_ashr_i32 s37, s36, 31
	s_lshl_b64 s[4:5], s[36:37], 19
	s_add_u32 s38, s18, s4
	s_addc_u32 s39, s19, s5
	s_and_b64 s[4:5], s[8:9], exec
	s_cselect_b32 s4, s39, s59
	s_cselect_b32 s5, s38, s58
	s_ashr_i32 s35, s34, 31
	s_lshl_b64 s[50:51], s[34:35], 19
	s_add_u32 s90, s1, s50
	s_addc_u32 s91, s14, s51
	s_and_b64 s[50:51], s[8:9], exec
	s_cselect_b32 s35, s91, s57
	s_cselect_b32 s37, s90, s56
	s_add_u32 s41, s56, 0x100
	s_addc_u32 s49, s57, 0
	s_add_u32 s92, s58, 0x40080
	s_addc_u32 s93, s59, 0
	s_mov_b32 s50, -2
	v_add_u32_e32 v134, 0x10000, v185
	v_add_u32_e32 v158, 0x14000, v185
	ds_read_b128 v[74:77], v134
	ds_read_b128 v[94:97], v134 offset:1024
	ds_read_b128 v[114:117], v134 offset:2048
	ds_read_b128 v[134:137], v134 offset:3072
	ds_read_b128 v[146:149], v158
	ds_read_b128 v[150:153], v158 offset:1024
	ds_read_b128 v[154:157], v158 offset:2048
	ds_read_b128 v[158:161], v158 offset:3072
	s_add_u32 s30, s92, 0xfffc0080
	s_addc_u32 s31, s93, -1
	s_cmp_eq_u32 s50, 12
	s_cselect_b32 s60, s5, s30
	s_cselect_b32 s61, s4, s31
	s_cselect_b32 s58, s37, s41
	s_cselect_b32 s59, s35, s49
	s_add_u32 s56, s60, 0x80
	s_addc_u32 s57, s61, 0
	ds_read_b128 v[162:165], v186
	ds_read_b128 v[166:169], v186 offset:1024
	ds_read_b128 v[170:173], v186 offset:2048
	ds_read_b128 v[174:177], v186 offset:3072
	ds_read_b128 v[188:191], v186 offset:4096
	ds_read_b128 v[202:205], v186 offset:5120
	ds_read_b128 v[206:209], v186 offset:6144
	ds_read_b128 v[210:213], v186 offset:7168
	s_mov_b32 m0, s67
	s_nop 0
	global_load_lds_dwordx4 v0, s[92:93]
	s_nop 0
	s_mov_b32 m0, s65
	s_nop 0
	global_load_lds_dwordx4 v181, s[92:93]
	s_waitcnt vmcnt(8)
	s_waitcnt lgkmcnt(0)
	s_barrier
	s_setprio 1
	s_waitcnt lgkmcnt(0)
	v_mfma_f32_16x16x32_bf16 v[142:145], v[74:77], v[162:165], 0
	v_mfma_f32_16x16x32_bf16 v[142:145], v[94:97], v[166:169], v[142:145]
	v_mfma_f32_16x16x32_bf16 v[138:141], v[114:117], v[162:165], 0
	v_mfma_f32_16x16x32_bf16 v[138:141], v[134:137], v[166:169], v[138:141]
	v_mfma_f32_16x16x32_bf16 v[130:133], v[146:149], v[162:165], 0
	v_mfma_f32_16x16x32_bf16 v[130:133], v[150:153], v[166:169], v[130:133]
	v_mfma_f32_16x16x32_bf16 v[126:129], v[154:157], v[162:165], 0
	v_mfma_f32_16x16x32_bf16 v[126:129], v[158:161], v[166:169], v[126:129]
	v_mfma_f32_16x16x32_bf16 v[106:109], v[154:157], v[170:173], 0
	v_mfma_f32_16x16x32_bf16 v[106:109], v[158:161], v[174:177], v[106:109]
	v_mfma_f32_16x16x32_bf16 v[110:113], v[146:149], v[170:173], 0
	v_mfma_f32_16x16x32_bf16 v[110:113], v[150:153], v[174:177], v[110:113]
	v_mfma_f32_16x16x32_bf16 v[118:121], v[114:117], v[170:173], 0
	v_mfma_f32_16x16x32_bf16 v[118:121], v[134:137], v[174:177], v[118:121]
	v_mfma_f32_16x16x32_bf16 v[122:125], v[74:77], v[170:173], 0
	v_mfma_f32_16x16x32_bf16 v[122:125], v[94:97], v[174:177], v[122:125]
	v_mfma_f32_16x16x32_bf16 v[102:105], v[74:77], v[188:191], 0
	v_mfma_f32_16x16x32_bf16 v[102:105], v[94:97], v[202:205], v[102:105]
	v_mfma_f32_16x16x32_bf16 v[98:101], v[114:117], v[188:191], 0
	v_mfma_f32_16x16x32_bf16 v[98:101], v[134:137], v[202:205], v[98:101]
	v_mfma_f32_16x16x32_bf16 v[90:93], v[146:149], v[188:191], 0
	v_mfma_f32_16x16x32_bf16 v[90:93], v[150:153], v[202:205], v[90:93]
	v_mfma_f32_16x16x32_bf16 v[86:89], v[154:157], v[188:191], 0
	v_mfma_f32_16x16x32_bf16 v[86:89], v[158:161], v[202:205], v[86:89]
	v_mfma_f32_16x16x32_bf16 v[66:69], v[154:157], v[206:209], 0
	v_mfma_f32_16x16x32_bf16 v[66:69], v[158:161], v[210:213], v[66:69]
	v_mfma_f32_16x16x32_bf16 v[70:73], v[146:149], v[206:209], 0
	v_mfma_f32_16x16x32_bf16 v[70:73], v[150:153], v[210:213], v[70:73]
	v_mfma_f32_16x16x32_bf16 v[78:81], v[114:117], v[206:209], 0
	v_mfma_f32_16x16x32_bf16 v[78:81], v[134:137], v[210:213], v[78:81]
	v_mfma_f32_16x16x32_bf16 v[82:85], v[74:77], v[206:209], 0
	v_mfma_f32_16x16x32_bf16 v[82:85], v[94:97], v[210:213], v[82:85]
	s_setprio 0
	s_barrier
	ds_read_b128 v[162:165], v186 offset:16384
	ds_read_b128 v[166:169], v186 offset:17408
	ds_read_b128 v[170:173], v186 offset:18432
	ds_read_b128 v[174:177], v186 offset:19456
	ds_read_b128 v[188:191], v186 offset:20480
	ds_read_b128 v[202:205], v186 offset:21504
	ds_read_b128 v[206:209], v186 offset:22528
	ds_read_b128 v[210:213], v186 offset:23552
	s_mov_b32 m0, s29
	s_nop 0
	global_load_lds_dwordx4 v180, s[58:59]
	s_add_u32 s30, s58, 0x40000
	s_mov_b32 m0, s42
	s_nop 0
	global_load_lds_dwordx4 v182, s[58:59]
	s_addc_u32 s31, s59, 0
	s_mov_b32 m0, s43
	s_nop 0
	global_load_lds_dwordx4 v180, s[30:31]
	s_nop 0
	s_mov_b32 m0, s44
	s_nop 0
	global_load_lds_dwordx4 v182, s[30:31]
	s_nop 0
	s_mov_b32 m0, s15
	s_nop 0
	global_load_lds_dwordx4 v0, s[60:61]
	s_nop 0
	s_mov_b32 m0, s45
	s_nop 0
	global_load_lds_dwordx4 v181, s[60:61]
	s_waitcnt vmcnt(8)
	s_waitcnt lgkmcnt(0)
	s_barrier
; #define PG8_STAGE(bufoff, gbase, voff) do { _Pragma("unroll") for (int _i = 0; _i < 2; ++_i) { \
;         const unsigned _m0 = ldsb + (unsigned)((bufoff) + _i * 8192); const char* _gb = (const char*)(gbase); \
;         asm volatile("s_mov_b32 m0, %0\n\ts_nop 0\n\tglobal_load_lds_dwordx4 %1, %2" :: "s"(_m0), "v"((voff)[_i]), "s"(_gb) : "m0", "memory"); } } while (0)
; #define PG8_LDA(dst, b, h) do { _Pragma("unroll") for (int m = 0; m < 4; ++m) _Pragma("unroll") for (int k = 0; k < 2; ++k) dst[m][k] = *(const LAS bf16x8*)(lds + PG8_SA(b, h) + aoff + m * 2048 + k * 1024); } while (0)
; #define PG8_LDB(dst, b, h) do { _Pragma("unroll") for (int n = 0; n < 2; ++n) _Pragma("unroll") for (int k = 0; k < 2; ++k) dst[n][k] = *(const LAS bf16x8*)(lds + PG8_SB(b, h) + boff + n * 2048 + k * 1024); } while (0)
; #define PG8_MMA(ai, bj, At, Bt) do { __builtin_amdgcn_s_setprio(1); _Pragma("unroll") for (int m = 0; m < 4; ++m) _Pragma("unroll") for (int n = 0; n < 2; ++n) _Pragma("unroll") for (int k = 0; k < 2; ++k) \
;         acc[ai][bj][m][n] = __builtin_amdgcn_mfma_f32_16x16x32_bf16(Bt[n][k], At[m][k], acc[ai][bj][m][n], 0, 0, 0); __builtin_amdgcn_s_setprio(0); } while (0)
; #define PG8_WAIT_V(n) asm volatile("s_waitcnt vmcnt(" #n ")" ::: "memory")
; #define PG8_WAIT_L(n) asm volatile("s_waitcnt lgkmcnt(" #n ")" ::: "memory")
; #define PG8_BAR __builtin_amdgcn_s_barrier()
; #define PG8_SCHED __builtin_amdgcn_sched_barrier(0)
; template <class Epi, bool ALIGN_EPI>
; __device__ __forceinline__ void gemm_phase(LAS unsigned char* lds, const Gemm g, const StaticOrder& S, const Epi& E) {
;     ...
;             PG8_WAIT_V(8); PG8_WAIT_L(0); PG8_BAR; PG8_MMA(1, 0, At, B0); PG8_MMA(1, 1, At, B1); PG8_BAR; PG8_SCHED;
;             PG8_LDB(B0, 1, 0); PG8_LDB(B1, 1, 1); PG8_SCHED; PG8_LDA(At, 1, 0); PG8_STAGE(PG8_SA(0, 1), a2 + hstepA, voffA);
;             PG8_WAIT_V(8); PG8_WAIT_L(0); PG8_BAR; PG8_MMA(0, 0, At, B0); PG8_MMA(0, 1, At, B1); PG8_BAR; PG8_SCHED;
;             PG8_LDA(At, 1, 1); PG8_STAGE(PG8_SB(1, 0), b3, voffB); PG8_STAGE(PG8_SB(1, 1), b3 + hstepB, voffB); PG8_STAGE(PG8_SA(1, 0), a3, voffA);
;             PG8_WAIT_V(8); PG8_WAIT_L(0); PG8_BAR; PG8_MMA(1, 0, At, B0); PG8_MMA(1, 1, At, B1); PG8_BAR; PG8_SCHED;
	s_setprio 1
	s_waitcnt lgkmcnt(0)
	v_mfma_f32_16x16x32_bf16 v[62:65], v[74:77], v[162:165], 0
	v_mfma_f32_16x16x32_bf16 v[62:65], v[94:97], v[166:169], v[62:65]
	v_mfma_f32_16x16x32_bf16 v[58:61], v[114:117], v[162:165], 0
	v_mfma_f32_16x16x32_bf16 v[58:61], v[134:137], v[166:169], v[58:61]
	v_mfma_f32_16x16x32_bf16 v[54:57], v[146:149], v[162:165], 0
	v_mfma_f32_16x16x32_bf16 v[54:57], v[150:153], v[166:169], v[54:57]
	v_mfma_f32_16x16x32_bf16 v[50:53], v[154:157], v[162:165], 0
	v_mfma_f32_16x16x32_bf16 v[50:53], v[158:161], v[166:169], v[50:53]
	v_mfma_f32_16x16x32_bf16 v[34:37], v[154:157], v[170:173], 0
	v_mfma_f32_16x16x32_bf16 v[34:37], v[158:161], v[174:177], v[34:37]
	v_mfma_f32_16x16x32_bf16 v[38:41], v[146:149], v[170:173], 0
	v_mfma_f32_16x16x32_bf16 v[38:41], v[150:153], v[174:177], v[38:41]
	v_mfma_f32_16x16x32_bf16 v[42:45], v[114:117], v[170:173], 0
	v_mfma_f32_16x16x32_bf16 v[42:45], v[134:137], v[174:177], v[42:45]
	v_mfma_f32_16x16x32_bf16 v[46:49], v[74:77], v[170:173], 0
	v_mfma_f32_16x16x32_bf16 v[46:49], v[94:97], v[174:177], v[46:49]
	v_mfma_f32_16x16x32_bf16 v[30:33], v[74:77], v[188:191], 0
	v_mfma_f32_16x16x32_bf16 v[30:33], v[94:97], v[202:205], v[30:33]
	v_mfma_f32_16x16x32_bf16 v[26:29], v[114:117], v[188:191], 0
	v_mfma_f32_16x16x32_bf16 v[26:29], v[134:137], v[202:205], v[26:29]
	v_mfma_f32_16x16x32_bf16 v[22:25], v[146:149], v[188:191], 0
	v_mfma_f32_16x16x32_bf16 v[22:25], v[150:153], v[202:205], v[22:25]
	v_mfma_f32_16x16x32_bf16 v[18:21], v[154:157], v[188:191], 0
	v_mfma_f32_16x16x32_bf16 v[18:21], v[158:161], v[202:205], v[18:21]
	v_mfma_f32_16x16x32_bf16 v[2:5], v[154:157], v[206:209], 0
	v_mfma_f32_16x16x32_bf16 v[2:5], v[158:161], v[210:213], v[2:5]
	v_mfma_f32_16x16x32_bf16 v[6:9], v[146:149], v[206:209], 0
	v_mfma_f32_16x16x32_bf16 v[6:9], v[150:153], v[210:213], v[6:9]
	v_mfma_f32_16x16x32_bf16 v[10:13], v[114:117], v[206:209], 0
	v_mfma_f32_16x16x32_bf16 v[10:13], v[134:137], v[210:213], v[10:13]
	v_mfma_f32_16x16x32_bf16 v[14:17], v[74:77], v[206:209], 0
	v_mfma_f32_16x16x32_bf16 v[14:17], v[94:97], v[210:213], v[14:17]
	s_setprio 0
	s_barrier
	v_add_u32_e32 v134, 0x18000, v185
	v_add_u32_e32 v158, 0x1c000, v185
	ds_read_b128 v[74:77], v134
	ds_read_b128 v[94:97], v134 offset:1024
	ds_read_b128 v[114:117], v134 offset:2048
	ds_read_b128 v[134:137], v134 offset:3072
	ds_read_b128 v[146:149], v158
	ds_read_b128 v[150:153], v158 offset:1024
	ds_read_b128 v[154:157], v158 offset:2048
	ds_read_b128 v[158:161], v158 offset:3072
	ds_read_b128 v[162:165], v186 offset:32768
	ds_read_b128 v[166:169], v186 offset:33792
	ds_read_b128 v[170:173], v186 offset:34816
	ds_read_b128 v[174:177], v186 offset:35840
	ds_read_b128 v[188:191], v186 offset:36864
	ds_read_b128 v[202:205], v186 offset:37888
	ds_read_b128 v[206:209], v186 offset:38912
	ds_read_b128 v[210:213], v186 offset:39936
	s_add_u32 s30, s60, 0x40000
	s_addc_u32 s31, s61, 0
	s_mov_b32 m0, s55
	s_nop 0
	global_load_lds_dwordx4 v0, s[30:31]
	s_nop 0
	s_mov_b32 m0, s88
	s_nop 0
	global_load_lds_dwordx4 v181, s[30:31]
	s_waitcnt vmcnt(8)
	s_waitcnt lgkmcnt(0)
	s_barrier
	s_setprio 1
	s_waitcnt lgkmcnt(0)
	v_mfma_f32_16x16x32_bf16 v[142:145], v[74:77], v[162:165], v[142:145]
	v_mfma_f32_16x16x32_bf16 v[142:145], v[94:97], v[166:169], v[142:145]
	v_mfma_f32_16x16x32_bf16 v[138:141], v[114:117], v[162:165], v[138:141]
	v_mfma_f32_16x16x32_bf16 v[138:141], v[134:137], v[166:169], v[138:141]
	v_mfma_f32_16x16x32_bf16 v[130:133], v[146:149], v[162:165], v[130:133]
	v_mfma_f32_16x16x32_bf16 v[130:133], v[150:153], v[166:169], v[130:133]
	v_mfma_f32_16x16x32_bf16 v[126:129], v[154:157], v[162:165], v[126:129]
	v_mfma_f32_16x16x32_bf16 v[126:129], v[158:161], v[166:169], v[126:129]
	v_mfma_f32_16x16x32_bf16 v[106:109], v[154:157], v[170:173], v[106:109]
	v_mfma_f32_16x16x32_bf16 v[106:109], v[158:161], v[174:177], v[106:109]
	v_mfma_f32_16x16x32_bf16 v[110:113], v[146:149], v[170:173], v[110:113]
	v_mfma_f32_16x16x32_bf16 v[110:113], v[150:153], v[174:177], v[110:113]
	v_mfma_f32_16x16x32_bf16 v[118:121], v[114:117], v[170:173], v[118:121]
	v_mfma_f32_16x16x32_bf16 v[118:121], v[134:137], v[174:177], v[118:121]
	v_mfma_f32_16x16x32_bf16 v[122:125], v[74:77], v[170:173], v[122:125]
	v_mfma_f32_16x16x32_bf16 v[122:125], v[94:97], v[174:177], v[122:125]
	v_mfma_f32_16x16x32_bf16 v[102:105], v[74:77], v[188:191], v[102:105]
	v_mfma_f32_16x16x32_bf16 v[102:105], v[94:97], v[202:205], v[102:105]
	v_mfma_f32_16x16x32_bf16 v[98:101], v[114:117], v[188:191], v[98:101]
	v_mfma_f32_16x16x32_bf16 v[98:101], v[134:137], v[202:205], v[98:101]
	v_mfma_f32_16x16x32_bf16 v[90:93], v[146:149], v[188:191], v[90:93]
	v_mfma_f32_16x16x32_bf16 v[90:93], v[150:153], v[202:205], v[90:93]
	v_mfma_f32_16x16x32_bf16 v[86:89], v[154:157], v[188:191], v[86:89]
	v_mfma_f32_16x16x32_bf16 v[86:89], v[158:161], v[202:205], v[86:89]
	v_mfma_f32_16x16x32_bf16 v[66:69], v[154:157], v[206:209], v[66:69]
	v_mfma_f32_16x16x32_bf16 v[66:69], v[158:161], v[210:213], v[66:69]
	v_mfma_f32_16x16x32_bf16 v[70:73], v[146:149], v[206:209], v[70:73]
	v_mfma_f32_16x16x32_bf16 v[70:73], v[150:153], v[210:213], v[70:73]
	v_mfma_f32_16x16x32_bf16 v[78:81], v[114:117], v[206:209], v[78:81]
	v_mfma_f32_16x16x32_bf16 v[78:81], v[134:137], v[210:213], v[78:81]
	v_mfma_f32_16x16x32_bf16 v[82:85], v[74:77], v[206:209], v[82:85]
	v_mfma_f32_16x16x32_bf16 v[82:85], v[94:97], v[210:213], v[82:85]
	s_setprio 0
	s_barrier
; #define PG8_STAGE(bufoff, gbase, voff) do { _Pragma("unroll") for (int _i = 0; _i < 2; ++_i) { \
;         const unsigned _m0 = ldsb + (unsigned)((bufoff) + _i * 8192); const char* _gb = (const char*)(gbase); \
;         asm volatile("s_mov_b32 m0, %0\n\ts_nop 0\n\tglobal_load_lds_dwordx4 %1, %2" :: "s"(_m0), "v"((voff)[_i]), "s"(_gb) : "m0", "memory"); } } while (0)
; #define PG8_LDA(dst, b, h) do { _Pragma("unroll") for (int m = 0; m < 4; ++m) _Pragma("unroll") for (int k = 0; k < 2; ++k) dst[m][k] = *(const LAS bf16x8*)(lds + PG8_SA(b, h) + aoff + m * 2048 + k * 1024); } while (0)
; #define PG8_MMA(ai, bj, At, Bt) do { __builtin_amdgcn_s_setprio(1); _Pragma("unroll") for (int m = 0; m < 4; ++m) _Pragma("unroll") for (int n = 0; n < 2; ++n) _Pragma("unroll") for (int k = 0; k < 2; ++k) \
;         acc[ai][bj][m][n] = __builtin_amdgcn_mfma_f32_16x16x32_bf16(Bt[n][k], At[m][k], acc[ai][bj][m][n], 0, 0, 0); __builtin_amdgcn_s_setprio(0); } while (0)
; #define PG8_WAIT_V(n) asm volatile("s_waitcnt vmcnt(" #n ")" ::: "memory")
; #define PG8_WAIT_L(n) asm volatile("s_waitcnt lgkmcnt(" #n ")" ::: "memory")
; #define PG8_BAR __builtin_amdgcn_s_barrier()
; #define PG8_SCHED __builtin_amdgcn_sched_barrier(0)
; template <class Epi, bool ALIGN_EPI>
; __device__ __forceinline__ void gemm_phase(LAS unsigned char* lds, const Gemm g, const StaticOrder& S, const Epi& E) {
;     ...
;             PG8_LDA(At, 1, 1); PG8_STAGE(PG8_SB(1, 0), b3, voffB); PG8_STAGE(PG8_SB(1, 1), b3 + hstepB, voffB); PG8_STAGE(PG8_SA(1, 0), a3, voffA);
;             PG8_WAIT_V(8); PG8_WAIT_L(0); PG8_BAR; PG8_MMA(1, 0, At, B0); PG8_MMA(1, 1, At, B1); PG8_BAR; PG8_SCHED;
;         }
	ds_read_b128 v[162:165], v186 offset:49152
	ds_read_b128 v[166:169], v186 offset:50176
	ds_read_b128 v[170:173], v186 offset:51200
	ds_read_b128 v[174:177], v186 offset:52224
	ds_read_b128 v[188:191], v186 offset:53248
	ds_read_b128 v[202:205], v186 offset:54272
	ds_read_b128 v[206:209], v186 offset:55296
	ds_read_b128 v[210:213], v186 offset:56320
	s_add_u32 s30, s58, 0x80
	s_addc_u32 s31, s59, 0
	s_mov_b32 m0, s94
	s_nop 0
	global_load_lds_dwordx4 v180, s[30:31]
	s_nop 0
	s_mov_b32 m0, s95
	s_nop 0
	global_load_lds_dwordx4 v182, s[30:31]
	s_add_u32 s30, s58, 0x40080
	s_addc_u32 s31, s59, 0
	s_mov_b32 m0, s17
	s_nop 0
	global_load_lds_dwordx4 v180, s[30:31]
	s_nop 0
	s_mov_b32 m0, s53
	s_nop 0
	global_load_lds_dwordx4 v182, s[30:31]
	s_nop 0
	s_mov_b32 m0, s96
	s_nop 0
	global_load_lds_dwordx4 v0, s[56:57]
	s_nop 0
	s_mov_b32 m0, s97
	s_nop 0
	global_load_lds_dwordx4 v181, s[56:57]
	s_waitcnt vmcnt(8)
	s_waitcnt lgkmcnt(0)
	s_barrier
	s_setprio 1
	s_waitcnt lgkmcnt(0)
	v_mfma_f32_16x16x32_bf16 v[62:65], v[74:77], v[162:165], v[62:65]
	v_mfma_f32_16x16x32_bf16 v[62:65], v[94:97], v[166:169], v[62:65]
	v_mfma_f32_16x16x32_bf16 v[58:61], v[114:117], v[162:165], v[58:61]
	v_mfma_f32_16x16x32_bf16 v[58:61], v[134:137], v[166:169], v[58:61]
	v_mfma_f32_16x16x32_bf16 v[54:57], v[146:149], v[162:165], v[54:57]
	v_mfma_f32_16x16x32_bf16 v[54:57], v[150:153], v[166:169], v[54:57]
	v_mfma_f32_16x16x32_bf16 v[50:53], v[154:157], v[162:165], v[50:53]
	v_mfma_f32_16x16x32_bf16 v[50:53], v[158:161], v[166:169], v[50:53]
	v_mfma_f32_16x16x32_bf16 v[34:37], v[154:157], v[170:173], v[34:37]
	v_mfma_f32_16x16x32_bf16 v[34:37], v[158:161], v[174:177], v[34:37]
	v_mfma_f32_16x16x32_bf16 v[38:41], v[146:149], v[170:173], v[38:41]
	v_mfma_f32_16x16x32_bf16 v[38:41], v[150:153], v[174:177], v[38:41]
	v_mfma_f32_16x16x32_bf16 v[42:45], v[114:117], v[170:173], v[42:45]
	v_mfma_f32_16x16x32_bf16 v[42:45], v[134:137], v[174:177], v[42:45]
	v_mfma_f32_16x16x32_bf16 v[46:49], v[74:77], v[170:173], v[46:49]
	v_mfma_f32_16x16x32_bf16 v[46:49], v[94:97], v[174:177], v[46:49]
	v_mfma_f32_16x16x32_bf16 v[30:33], v[74:77], v[188:191], v[30:33]
	v_mfma_f32_16x16x32_bf16 v[30:33], v[94:97], v[202:205], v[30:33]
	v_mfma_f32_16x16x32_bf16 v[26:29], v[114:117], v[188:191], v[26:29]
	v_mfma_f32_16x16x32_bf16 v[26:29], v[134:137], v[202:205], v[26:29]
	v_mfma_f32_16x16x32_bf16 v[22:25], v[146:149], v[188:191], v[22:25]
	v_mfma_f32_16x16x32_bf16 v[22:25], v[150:153], v[202:205], v[22:25]
	v_mfma_f32_16x16x32_bf16 v[18:21], v[154:157], v[188:191], v[18:21]
	v_mfma_f32_16x16x32_bf16 v[18:21], v[158:161], v[202:205], v[18:21]
	v_mfma_f32_16x16x32_bf16 v[2:5], v[154:157], v[206:209], v[2:5]
	v_mfma_f32_16x16x32_bf16 v[2:5], v[158:161], v[210:213], v[2:5]
	v_mfma_f32_16x16x32_bf16 v[6:9], v[146:149], v[206:209], v[6:9]
	v_mfma_f32_16x16x32_bf16 v[6:9], v[150:153], v[210:213], v[6:9]
	v_mfma_f32_16x16x32_bf16 v[10:13], v[114:117], v[206:209], v[10:13]
	v_mfma_f32_16x16x32_bf16 v[10:13], v[134:137], v[210:213], v[10:13]
	v_mfma_f32_16x16x32_bf16 v[14:17], v[74:77], v[206:209], v[14:17]
	v_mfma_f32_16x16x32_bf16 v[14:17], v[94:97], v[210:213], v[14:17]
	s_setprio 0
	s_barrier
	s_add_i32 s50, s50, 2
	s_add_u32 s41, s41, 0x100
	s_addc_u32 s49, s49, 0
	s_add_u32 s92, s92, 0x100
	s_addc_u32 s93, s93, 0
	s_cmp_gt_u32 s50, 13

; __device__ __forceinline__ unsigned cvt_pk_bf16(float lo, float hi) { unsigned r; asm volatile("v_cvt_pk_bf16_f32 %0, %1, %2" : "=v"(r) : "v"(lo), "v"(hi)); return r; }
; __device__ __forceinline__ float silu_f(float g) { return g * __builtin_amdgcn_rcpf(1.0f + __builtin_amdgcn_exp2f(g * -1.4426950408889634f)); }
; __device__ __forceinline__ void rstd8(const float* ss, int row0, float (&rs)[2][4]) {
;     f32x4 p[2][4];
; #pragma unroll
;     for (int ai = 0; ai < 2; ++ai)
; #pragma unroll
;         for (int m = 0; m < 4; ++m) p[ai][m] = *(const f32x4*)(ss + 4 * (size_t)(row0 + ai * HALF + m * 16));
; #pragma unroll
;     for (int ai = 0; ai < 2; ++ai)
; #pragma unroll
;         for (int m = 0; m < 4; ++m) rs[ai][m] = __builtin_amdgcn_rsqf(((p[ai][m].x + p[ai][m].y) + (p[ai][m].z + p[ai][m].w)) * (1.0f / D) + EPS);
; }
;     __device__ __forceinline__ void operator()(const f32x4 (&acc)[2][2][4][2], const Unit& u, int wr, int wc, int fr, int fq) const {
;         const int row0 = u.pm * BM + wr * 64 + fr, col0 = u.pn * HALF + wc * 32 + 8 * fq;
;         float rsv[2][4]; rstd8(ss, row0, rsv);
; #pragma unroll
;         for (int ai = 0; ai < 2; ++ai)
; #pragma unroll
;             for (int m = 0; m < 4; ++m) { const int row = row0 + ai * HALF + m * 16; const float rs = rsv[ai][m];
;                 f32x4 g0 = acc[ai][0][m][0] * rs, g1 = acc[ai][0][m][1] * rs; const f32x4 t0 = acc[ai][1][m][0] * rs, t1 = acc[ai][1][m][1] * rs;
;                 if (silu) {
; #pragma unroll
;                     for (int j = 0; j < 4; ++j) { g0[j] = silu_f(g0[j]); g1[j] = silu_f(g1[j]); } }
;                 g0 = g0 * t0; g1 = g1 * t1;
;                 u32x4 w; w.x = cvt_pk_bf16(g0[0], g0[1]); w.y = cvt_pk_bf16(g0[2], g0[3]); w.z = cvt_pk_bf16(g1[0], g1[1]); w.w = cvt_pk_bf16(g1[2], g1[3]);
;                 *(u32x4*)(O + (size_t)row * ldc + col0 + (size_t)(row >> 12) * adj) = w; }
.Lep_fast:
	s_lshl_b32 s4, s54, 8
	s_add_i32 s4, s4, s89
	v_or_b32_e32 v178, s4, v183
	s_lshl_b32 s5, s0, 1
	v_lshl_or_b32 v179, s48, 7, v184
	s_lshl_b32 s30, s5, 4
	s_mul_i32 s31, s5, 80
	v_mul_lo_u32 v190, v178, s5
	s_cmp_eq_u32 s54, s98
	v_lshl_add_u32 v190, v179, 1, v190
	s_cbranch_scc1 .Lep_have_rs
	v_lshlrev_b32_e32 v178, 4, v178
	global_load_dwordx4 v[146:149], v178, s[24:25]
	global_load_dwordx4 v[150:153], v178, s[24:25] offset:256
	global_load_dwordx4 v[154:157], v178, s[24:25] offset:512
	global_load_dwordx4 v[158:161], v178, s[24:25] offset:768
	global_load_dwordx4 v[162:165], v178, s[24:25] offset:2048
	global_load_dwordx4 v[166:169], v178, s[24:25] offset:2304
	global_load_dwordx4 v[170:173], v178, s[24:25] offset:2560
	global_load_dwordx4 v[174:177], v178, s[24:25] offset:2816
	s_mov_b32 s98, s54
	s_waitcnt vmcnt(0)
	v_add_f32_e32 v146, v146, v147
	v_add_f32_e32 v148, v148, v149
	v_add_f32_e32 v150, v150, v151
	v_add_f32_e32 v152, v152, v153
	v_add_f32_e32 v154, v154, v155
	v_add_f32_e32 v156, v156, v157
	v_add_f32_e32 v158, v158, v159
	v_add_f32_e32 v160, v160, v161
	v_add_f32_e32 v162, v162, v163
	v_add_f32_e32 v164, v164, v165
	v_add_f32_e32 v166, v166, v167
	v_add_f32_e32 v168, v168, v169
	v_add_f32_e32 v170, v170, v171
	v_add_f32_e32 v172, v172, v173
	v_add_f32_e32 v174, v174, v175
	v_add_f32_e32 v176, v176, v177
	v_add_f32_e32 v146, v146, v148
	v_add_f32_e32 v150, v150, v152
	v_add_f32_e32 v154, v154, v156
	v_add_f32_e32 v158, v158, v160
	v_add_f32_e32 v162, v162, v164
	v_add_f32_e32 v166, v166, v168
	v_add_f32_e32 v170, v170, v172
	v_add_f32_e32 v174, v174, v176
	v_fmamk_f32 v241, v146, 0x3a800000, v224
	v_fmamk_f32 v243, v150, 0x3a800000, v224
	v_fmamk_f32 v245, v154, 0x3a800000, v224
	v_fmamk_f32 v247, v158, 0x3a800000, v224
	v_fmamk_f32 v249, v162, 0x3a800000, v224
	v_fmamk_f32 v251, v166, 0x3a800000, v224
	v_fmamk_f32 v253, v170, 0x3a800000, v224
	v_fmamk_f32 v215, v174, 0x3a800000, v224
	v_rsq_f32_e32 v240, v241
	v_rsq_f32_e32 v242, v243
	v_rsq_f32_e32 v244, v245
	v_rsq_f32_e32 v246, v247
	v_rsq_f32_e32 v248, v249
	v_rsq_f32_e32 v250, v251
	v_rsq_f32_e32 v252, v253
	v_rsq_f32_e32 v214, v215
	s_nop 0
	v_mul_f32_e32 v240, 0xbfb8aa3b, v240
	v_mul_f32_e32 v242, 0xbfb8aa3b, v242
	v_mul_f32_e32 v244, 0xbfb8aa3b, v244
	v_mul_f32_e32 v246, 0xbfb8aa3b, v246
	v_mul_f32_e32 v248, 0xbfb8aa3b, v248
	v_mul_f32_e32 v250, 0xbfb8aa3b, v250
	v_mul_f32_e32 v252, 0xbfb8aa3b, v252
	v_mul_f32_e32 v214, 0xbfb8aa3b, v214
.Lep_have_rs:
	v_pk_mul_f32 v[146:147], v[142:143], v[240:241] op_sel_hi:[1,0]
	v_pk_mul_f32 v[148:149], v[144:145], v[240:241] op_sel_hi:[1,0]
	v_pk_mul_f32 v[150:151], v[138:139], v[240:241] op_sel_hi:[1,0]
	v_pk_mul_f32 v[152:153], v[140:141], v[240:241] op_sel_hi:[1,0]
	v_exp_f32_e32 v146, v146
	v_exp_f32_e32 v147, v147
	v_exp_f32_e32 v148, v148
	v_exp_f32_e32 v149, v149
	v_exp_f32_e32 v150, v150
	v_exp_f32_e32 v151, v151
	v_exp_f32_e32 v152, v152
	v_exp_f32_e32 v153, v153
	v_pk_mul_f32 v[142:143], v[142:143], v[130:131]
	v_pk_mul_f32 v[144:145], v[144:145], v[132:133]
	v_pk_mul_f32 v[138:139], v[138:139], v[126:127]
	v_pk_mul_f32 v[140:141], v[140:141], v[128:129]
	v_pk_fma_f32 v[146:147], v[146:147], v[240:241], v[240:241] op_sel:[0,1,1] op_sel_hi:[1,1,1]
	v_pk_fma_f32 v[148:149], v[148:149], v[240:241], v[240:241] op_sel:[0,1,1] op_sel_hi:[1,1,1]
	v_pk_fma_f32 v[150:151], v[150:151], v[240:241], v[240:241] op_sel:[0,1,1] op_sel_hi:[1,1,1]
	v_pk_fma_f32 v[152:153], v[152:153], v[240:241], v[240:241] op_sel:[0,1,1] op_sel_hi:[1,1,1]
	v_rcp_f32_e32 v146, v146
	v_rcp_f32_e32 v147, v147
	v_rcp_f32_e32 v148, v148
	v_rcp_f32_e32 v149, v149
	v_rcp_f32_e32 v150, v150
	v_rcp_f32_e32 v151, v151
	v_rcp_f32_e32 v152, v152
	v_rcp_f32_e32 v153, v153
	v_pk_mul_f32 v[154:155], v[122:123], v[242:243] op_sel_hi:[1,0]
	v_pk_mul_f32 v[156:157], v[124:125], v[242:243] op_sel_hi:[1,0]
	v_pk_mul_f32 v[158:159], v[118:119], v[242:243] op_sel_hi:[1,0]
	v_pk_mul_f32 v[160:161], v[120:121], v[242:243] op_sel_hi:[1,0]
	v_pk_mul_f32 v[142:143], v[142:143], v[146:147]
	v_pk_mul_f32 v[144:145], v[144:145], v[148:149]
	v_pk_mul_f32 v[138:139], v[138:139], v[150:151]
	v_pk_mul_f32 v[140:141], v[140:141], v[152:153]
	v_cvt_pk_bf16_f32 v162, v142, v143
	v_cvt_pk_bf16_f32 v163, v144, v145
	v_cvt_pk_bf16_f32 v164, v138, v139
	v_cvt_pk_bf16_f32 v165, v140, v141
	global_store_dwordx4 v190, v[162:165], s[10:11]
	v_add_u32_e32 v190, s30, v190
	v_exp_f32_e32 v154, v154
	v_exp_f32_e32 v155, v155
	v_exp_f32_e32 v156, v156
	v_exp_f32_e32 v157, v157
	v_exp_f32_e32 v158, v158
	v_exp_f32_e32 v159, v159
	v_exp_f32_e32 v160, v160
	v_exp_f32_e32 v161, v161
	v_pk_mul_f32 v[122:123], v[122:123], v[110:111]
	v_pk_mul_f32 v[124:125], v[124:125], v[112:113]
	v_pk_mul_f32 v[118:119], v[118:119], v[106:107]
	v_pk_mul_f32 v[120:121], v[120:121], v[108:109]
	v_pk_fma_f32 v[154:155], v[154:155], v[242:243], v[242:243] op_sel:[0,1,1] op_sel_hi:[1,1,1]
	v_pk_fma_f32 v[156:157], v[156:157], v[242:243], v[242:243] op_sel:[0,1,1] op_sel_hi:[1,1,1]
	v_pk_fma_f32 v[158:159], v[158:159], v[242:243], v[242:243] op_sel:[0,1,1] op_sel_hi:[1,1,1]
	v_pk_fma_f32 v[160:161], v[160:161], v[242:243], v[242:243] op_sel:[0,1,1] op_sel_hi:[1,1,1]
	v_rcp_f32_e32 v154, v154
	v_rcp_f32_e32 v155, v155
	v_rcp_f32_e32 v156, v156
	v_rcp_f32_e32 v157, v157
	v_rcp_f32_e32 v158, v158
	v_rcp_f32_e32 v159, v159
	v_rcp_f32_e32 v160, v160
	v_rcp_f32_e32 v161, v161
	v_pk_mul_f32 v[146:147], v[102:103], v[244:245] op_sel_hi:[1,0]
	v_pk_mul_f32 v[148:149], v[104:105], v[244:245] op_sel_hi:[1,0]
	v_pk_mul_f32 v[150:151], v[98:99], v[244:245] op_sel_hi:[1,0]
	v_pk_mul_f32 v[152:153], v[100:101], v[244:245] op_sel_hi:[1,0]
; __device__ __forceinline__ unsigned cvt_pk_bf16(float lo, float hi) { unsigned r; asm volatile("v_cvt_pk_bf16_f32 %0, %1, %2" : "=v"(r) : "v"(lo), "v"(hi)); return r; }
; __device__ __forceinline__ float silu_f(float g) { return g * __builtin_amdgcn_rcpf(1.0f + __builtin_amdgcn_exp2f(g * -1.4426950408889634f)); }
;     __device__ __forceinline__ void operator()(const f32x4 (&acc)[2][2][4][2], const Unit& u, int wr, int wc, int fr, int fq) const {
;     ...
;             for (int m = 0; m < 4; ++m) { const int row = row0 + ai * HALF + m * 16; const float rs = rsv[ai][m];
;                 f32x4 g0 = acc[ai][0][m][0] * rs, g1 = acc[ai][0][m][1] * rs; const f32x4 t0 = acc[ai][1][m][0] * rs, t1 = acc[ai][1][m][1] * rs;
;                 if (silu) {
; #pragma unroll
;                     for (int j = 0; j < 4; ++j) { g0[j] = silu_f(g0[j]); g1[j] = silu_f(g1[j]); } }
;                 g0 = g0 * t0; g1 = g1 * t1;
;                 u32x4 w; w.x = cvt_pk_bf16(g0[0], g0[1]); w.y = cvt_pk_bf16(g0[2], g0[3]); w.z = cvt_pk_bf16(g1[0], g1[1]); w.w = cvt_pk_bf16(g1[2], g1[3]);
;                 *(u32x4*)(O + (size_t)row * ldc + col0 + (size_t)(row >> 12) * adj) = w; }
	v_pk_mul_f32 v[122:123], v[122:123], v[154:155]
	v_pk_mul_f32 v[124:125], v[124:125], v[156:157]
	v_pk_mul_f32 v[118:119], v[118:119], v[158:159]
	v_pk_mul_f32 v[120:121], v[120:121], v[160:161]
	v_cvt_pk_bf16_f32 v166, v122, v123
	v_cvt_pk_bf16_f32 v167, v124, v125
	v_cvt_pk_bf16_f32 v168, v118, v119
	v_cvt_pk_bf16_f32 v169, v120, v121
	global_store_dwordx4 v190, v[166:169], s[10:11]
	v_add_u32_e32 v190, s30, v190
	v_exp_f32_e32 v146, v146
	v_exp_f32_e32 v147, v147
	v_exp_f32_e32 v148, v148
	v_exp_f32_e32 v149, v149
	v_exp_f32_e32 v150, v150
	v_exp_f32_e32 v151, v151
	v_exp_f32_e32 v152, v152
	v_exp_f32_e32 v153, v153
	v_pk_mul_f32 v[102:103], v[102:103], v[90:91]
	v_pk_mul_f32 v[104:105], v[104:105], v[92:93]
	v_pk_mul_f32 v[98:99], v[98:99], v[86:87]
	v_pk_mul_f32 v[100:101], v[100:101], v[88:89]
	v_pk_fma_f32 v[146:147], v[146:147], v[244:245], v[244:245] op_sel:[0,1,1] op_sel_hi:[1,1,1]
	v_pk_fma_f32 v[148:149], v[148:149], v[244:245], v[244:245] op_sel:[0,1,1] op_sel_hi:[1,1,1]
	v_pk_fma_f32 v[150:151], v[150:151], v[244:245], v[244:245] op_sel:[0,1,1] op_sel_hi:[1,1,1]
	v_pk_fma_f32 v[152:153], v[152:153], v[244:245], v[244:245] op_sel:[0,1,1] op_sel_hi:[1,1,1]
	v_rcp_f32_e32 v146, v146
	v_rcp_f32_e32 v147, v147
	v_rcp_f32_e32 v148, v148
	v_rcp_f32_e32 v149, v149
	v_rcp_f32_e32 v150, v150
	v_rcp_f32_e32 v151, v151
	v_rcp_f32_e32 v152, v152
	v_rcp_f32_e32 v153, v153
	v_pk_mul_f32 v[154:155], v[82:83], v[246:247] op_sel_hi:[1,0]
	v_pk_mul_f32 v[156:157], v[84:85], v[246:247] op_sel_hi:[1,0]
	v_pk_mul_f32 v[158:159], v[78:79], v[246:247] op_sel_hi:[1,0]
	v_pk_mul_f32 v[160:161], v[80:81], v[246:247] op_sel_hi:[1,0]
	v_pk_mul_f32 v[102:103], v[102:103], v[146:147]
	v_pk_mul_f32 v[104:105], v[104:105], v[148:149]
	v_pk_mul_f32 v[98:99], v[98:99], v[150:151]
	v_pk_mul_f32 v[100:101], v[100:101], v[152:153]
	v_cvt_pk_bf16_f32 v162, v102, v103
	v_cvt_pk_bf16_f32 v163, v104, v105
	v_cvt_pk_bf16_f32 v164, v98, v99
	v_cvt_pk_bf16_f32 v165, v100, v101
	global_store_dwordx4 v190, v[162:165], s[10:11]
	v_add_u32_e32 v190, s30, v190
	v_exp_f32_e32 v154, v154
	v_exp_f32_e32 v155, v155
	v_exp_f32_e32 v156, v156
	v_exp_f32_e32 v157, v157
	v_exp_f32_e32 v158, v158
	v_exp_f32_e32 v159, v159
	v_exp_f32_e32 v160, v160
	v_exp_f32_e32 v161, v161
	v_pk_mul_f32 v[82:83], v[82:83], v[70:71]
	v_pk_mul_f32 v[84:85], v[84:85], v[72:73]
	v_pk_mul_f32 v[78:79], v[78:79], v[66:67]
	v_pk_mul_f32 v[80:81], v[80:81], v[68:69]
	v_pk_fma_f32 v[154:155], v[154:155], v[246:247], v[246:247] op_sel:[0,1,1] op_sel_hi:[1,1,1]
	v_pk_fma_f32 v[156:157], v[156:157], v[246:247], v[246:247] op_sel:[0,1,1] op_sel_hi:[1,1,1]
	v_pk_fma_f32 v[158:159], v[158:159], v[246:247], v[246:247] op_sel:[0,1,1] op_sel_hi:[1,1,1]
	v_pk_fma_f32 v[160:161], v[160:161], v[246:247], v[246:247] op_sel:[0,1,1] op_sel_hi:[1,1,1]
	v_rcp_f32_e32 v154, v154
	v_rcp_f32_e32 v155, v155
	v_rcp_f32_e32 v156, v156
	v_rcp_f32_e32 v157, v157
	v_rcp_f32_e32 v158, v158
	v_rcp_f32_e32 v159, v159
	v_rcp_f32_e32 v160, v160
	v_rcp_f32_e32 v161, v161
	v_pk_mul_f32 v[146:147], v[62:63], v[248:249] op_sel_hi:[1,0]
	v_pk_mul_f32 v[148:149], v[64:65], v[248:249] op_sel_hi:[1,0]
	v_pk_mul_f32 v[150:151], v[58:59], v[248:249] op_sel_hi:[1,0]
	v_pk_mul_f32 v[152:153], v[60:61], v[248:249] op_sel_hi:[1,0]
	v_pk_mul_f32 v[82:83], v[82:83], v[154:155]
	v_pk_mul_f32 v[84:85], v[84:85], v[156:157]
	v_pk_mul_f32 v[78:79], v[78:79], v[158:159]
	v_pk_mul_f32 v[80:81], v[80:81], v[160:161]
	v_cvt_pk_bf16_f32 v166, v82, v83
	v_cvt_pk_bf16_f32 v167, v84, v85
	v_cvt_pk_bf16_f32 v168, v78, v79
	v_cvt_pk_bf16_f32 v169, v80, v81
	global_store_dwordx4 v190, v[166:169], s[10:11]
	v_add_u32_e32 v190, s31, v190
	v_exp_f32_e32 v146, v146
	v_exp_f32_e32 v147, v147
	v_exp_f32_e32 v148, v148
	v_exp_f32_e32 v149, v149
	v_exp_f32_e32 v150, v150
	v_exp_f32_e32 v151, v151
	v_exp_f32_e32 v152, v152
	v_exp_f32_e32 v153, v153
	v_pk_mul_f32 v[62:63], v[62:63], v[54:55]
	v_pk_mul_f32 v[64:65], v[64:65], v[56:57]
	v_pk_mul_f32 v[58:59], v[58:59], v[50:51]
	v_pk_mul_f32 v[60:61], v[60:61], v[52:53]
	v_pk_fma_f32 v[146:147], v[146:147], v[248:249], v[248:249] op_sel:[0,1,1] op_sel_hi:[1,1,1]
	v_pk_fma_f32 v[148:149], v[148:149], v[248:249], v[248:249] op_sel:[0,1,1] op_sel_hi:[1,1,1]
	v_pk_fma_f32 v[150:151], v[150:151], v[248:249], v[248:249] op_sel:[0,1,1] op_sel_hi:[1,1,1]
	v_pk_fma_f32 v[152:153], v[152:153], v[248:249], v[248:249] op_sel:[0,1,1] op_sel_hi:[1,1,1]
	v_rcp_f32_e32 v146, v146
	v_rcp_f32_e32 v147, v147
	v_rcp_f32_e32 v148, v148
	v_rcp_f32_e32 v149, v149
	v_rcp_f32_e32 v150, v150
	v_rcp_f32_e32 v151, v151
	v_rcp_f32_e32 v152, v152
	v_rcp_f32_e32 v153, v153
	v_pk_mul_f32 v[154:155], v[46:47], v[250:251] op_sel_hi:[1,0]
	v_pk_mul_f32 v[156:157], v[48:49], v[250:251] op_sel_hi:[1,0]
	v_pk_mul_f32 v[158:159], v[42:43], v[250:251] op_sel_hi:[1,0]
	v_pk_mul_f32 v[160:161], v[44:45], v[250:251] op_sel_hi:[1,0]
	v_pk_mul_f32 v[62:63], v[62:63], v[146:147]
; __device__ __forceinline__ unsigned cvt_pk_bf16(float lo, float hi) { unsigned r; asm volatile("v_cvt_pk_bf16_f32 %0, %1, %2" : "=v"(r) : "v"(lo), "v"(hi)); return r; }
; __device__ __forceinline__ float silu_f(float g) { return g * __builtin_amdgcn_rcpf(1.0f + __builtin_amdgcn_exp2f(g * -1.4426950408889634f)); }
;     __device__ __forceinline__ void operator()(const f32x4 (&acc)[2][2][4][2], const Unit& u, int wr, int wc, int fr, int fq) const {
;     ...
;             for (int m = 0; m < 4; ++m) { const int row = row0 + ai * HALF + m * 16; const float rs = rsv[ai][m];
;                 f32x4 g0 = acc[ai][0][m][0] * rs, g1 = acc[ai][0][m][1] * rs; const f32x4 t0 = acc[ai][1][m][0] * rs, t1 = acc[ai][1][m][1] * rs;
;                 if (silu) {
; #pragma unroll
;                     for (int j = 0; j < 4; ++j) { g0[j] = silu_f(g0[j]); g1[j] = silu_f(g1[j]); } }
;                 g0 = g0 * t0; g1 = g1 * t1;
;                 u32x4 w; w.x = cvt_pk_bf16(g0[0], g0[1]); w.y = cvt_pk_bf16(g0[2], g0[3]); w.z = cvt_pk_bf16(g1[0], g1[1]); w.w = cvt_pk_bf16(g1[2], g1[3]);
;                 *(u32x4*)(O + (size_t)row * ldc + col0 + (size_t)(row >> 12) * adj) = w; }
	v_pk_mul_f32 v[64:65], v[64:65], v[148:149]
	v_pk_mul_f32 v[58:59], v[58:59], v[150:151]
	v_pk_mul_f32 v[60:61], v[60:61], v[152:153]
	v_cvt_pk_bf16_f32 v162, v62, v63
	v_cvt_pk_bf16_f32 v163, v64, v65
	v_cvt_pk_bf16_f32 v164, v58, v59
	v_cvt_pk_bf16_f32 v165, v60, v61
	global_store_dwordx4 v190, v[162:165], s[10:11]
	v_add_u32_e32 v190, s30, v190
	v_exp_f32_e32 v154, v154
	v_exp_f32_e32 v155, v155
	v_exp_f32_e32 v156, v156
	v_exp_f32_e32 v157, v157
	v_exp_f32_e32 v158, v158
	v_exp_f32_e32 v159, v159
	v_exp_f32_e32 v160, v160
	v_exp_f32_e32 v161, v161
	v_pk_mul_f32 v[46:47], v[46:47], v[38:39]
	v_pk_mul_f32 v[48:49], v[48:49], v[40:41]
	v_pk_mul_f32 v[42:43], v[42:43], v[34:35]
	v_pk_mul_f32 v[44:45], v[44:45], v[36:37]
	v_pk_fma_f32 v[154:155], v[154:155], v[250:251], v[250:251] op_sel:[0,1,1] op_sel_hi:[1,1,1]
	v_pk_fma_f32 v[156:157], v[156:157], v[250:251], v[250:251] op_sel:[0,1,1] op_sel_hi:[1,1,1]
	v_pk_fma_f32 v[158:159], v[158:159], v[250:251], v[250:251] op_sel:[0,1,1] op_sel_hi:[1,1,1]
	v_pk_fma_f32 v[160:161], v[160:161], v[250:251], v[250:251] op_sel:[0,1,1] op_sel_hi:[1,1,1]
	v_rcp_f32_e32 v154, v154
	v_rcp_f32_e32 v155, v155
	v_rcp_f32_e32 v156, v156
	v_rcp_f32_e32 v157, v157
	v_rcp_f32_e32 v158, v158
	v_rcp_f32_e32 v159, v159
	v_rcp_f32_e32 v160, v160
	v_rcp_f32_e32 v161, v161
	v_pk_mul_f32 v[146:147], v[30:31], v[252:253] op_sel_hi:[1,0]
	v_pk_mul_f32 v[148:149], v[32:33], v[252:253] op_sel_hi:[1,0]
	v_pk_mul_f32 v[150:151], v[26:27], v[252:253] op_sel_hi:[1,0]
	v_pk_mul_f32 v[152:153], v[28:29], v[252:253] op_sel_hi:[1,0]
	v_pk_mul_f32 v[46:47], v[46:47], v[154:155]
	v_pk_mul_f32 v[48:49], v[48:49], v[156:157]
	v_pk_mul_f32 v[42:43], v[42:43], v[158:159]
	v_pk_mul_f32 v[44:45], v[44:45], v[160:161]
	v_cvt_pk_bf16_f32 v166, v46, v47
	v_cvt_pk_bf16_f32 v167, v48, v49
	v_cvt_pk_bf16_f32 v168, v42, v43
	v_cvt_pk_bf16_f32 v169, v44, v45
	global_store_dwordx4 v190, v[166:169], s[10:11]
	v_add_u32_e32 v190, s30, v190
	v_exp_f32_e32 v146, v146
	v_exp_f32_e32 v147, v147
	v_exp_f32_e32 v148, v148
	v_exp_f32_e32 v149, v149
	v_exp_f32_e32 v150, v150
	v_exp_f32_e32 v151, v151
	v_exp_f32_e32 v152, v152
	v_exp_f32_e32 v153, v153
	v_pk_mul_f32 v[30:31], v[30:31], v[22:23]
	v_pk_mul_f32 v[32:33], v[32:33], v[24:25]
	v_pk_mul_f32 v[26:27], v[26:27], v[18:19]
	v_pk_mul_f32 v[28:29], v[28:29], v[20:21]
	v_pk_fma_f32 v[146:147], v[146:147], v[252:253], v[252:253] op_sel:[0,1,1] op_sel_hi:[1,1,1]
	v_pk_fma_f32 v[148:149], v[148:149], v[252:253], v[252:253] op_sel:[0,1,1] op_sel_hi:[1,1,1]
	v_pk_fma_f32 v[150:151], v[150:151], v[252:253], v[252:253] op_sel:[0,1,1] op_sel_hi:[1,1,1]
	v_pk_fma_f32 v[152:153], v[152:153], v[252:253], v[252:253] op_sel:[0,1,1] op_sel_hi:[1,1,1]
	v_rcp_f32_e32 v146, v146
	v_rcp_f32_e32 v147, v147
	v_rcp_f32_e32 v148, v148
	v_rcp_f32_e32 v149, v149
	v_rcp_f32_e32 v150, v150
	v_rcp_f32_e32 v151, v151
	v_rcp_f32_e32 v152, v152
	v_rcp_f32_e32 v153, v153
	v_pk_mul_f32 v[154:155], v[14:15], v[214:215] op_sel_hi:[1,0]
	v_pk_mul_f32 v[156:157], v[16:17], v[214:215] op_sel_hi:[1,0]
	v_pk_mul_f32 v[158:159], v[10:11], v[214:215] op_sel_hi:[1,0]
	v_pk_mul_f32 v[160:161], v[12:13], v[214:215] op_sel_hi:[1,0]
	v_pk_mul_f32 v[30:31], v[30:31], v[146:147]
	v_pk_mul_f32 v[32:33], v[32:33], v[148:149]
	v_pk_mul_f32 v[26:27], v[26:27], v[150:151]
	v_pk_mul_f32 v[28:29], v[28:29], v[152:153]
	v_cvt_pk_bf16_f32 v162, v30, v31
	v_cvt_pk_bf16_f32 v163, v32, v33
	v_cvt_pk_bf16_f32 v164, v26, v27
	v_cvt_pk_bf16_f32 v165, v28, v29
	global_store_dwordx4 v190, v[162:165], s[10:11]
	v_add_u32_e32 v190, s30, v190
	v_exp_f32_e32 v154, v154
	v_exp_f32_e32 v155, v155
	v_exp_f32_e32 v156, v156
	v_exp_f32_e32 v157, v157
	v_exp_f32_e32 v158, v158
	v_exp_f32_e32 v159, v159
	v_exp_f32_e32 v160, v160
	v_exp_f32_e32 v161, v161
	v_pk_mul_f32 v[14:15], v[14:15], v[6:7]
	v_pk_mul_f32 v[16:17], v[16:17], v[8:9]
	v_pk_mul_f32 v[10:11], v[10:11], v[2:3]
	v_pk_mul_f32 v[12:13], v[12:13], v[4:5]
	v_pk_fma_f32 v[154:155], v[154:155], v[214:215], v[214:215] op_sel:[0,1,1] op_sel_hi:[1,1,1]
	v_pk_fma_f32 v[156:157], v[156:157], v[214:215], v[214:215] op_sel:[0,1,1] op_sel_hi:[1,1,1]
	v_pk_fma_f32 v[158:159], v[158:159], v[214:215], v[214:215] op_sel:[0,1,1] op_sel_hi:[1,1,1]
	v_pk_fma_f32 v[160:161], v[160:161], v[214:215], v[214:215] op_sel:[0,1,1] op_sel_hi:[1,1,1]
	v_rcp_f32_e32 v154, v154
	v_rcp_f32_e32 v155, v155
	v_rcp_f32_e32 v156, v156
	v_rcp_f32_e32 v157, v157
	v_rcp_f32_e32 v158, v158
	v_rcp_f32_e32 v159, v159
	v_rcp_f32_e32 v160, v160
	v_rcp_f32_e32 v161, v161
	v_pk_mul_f32 v[14:15], v[14:15], v[154:155]
	v_pk_mul_f32 v[16:17], v[16:17], v[156:157]
	v_pk_mul_f32 v[10:11], v[10:11], v[158:159]
	v_pk_mul_f32 v[12:13], v[12:13], v[160:161]
	v_cvt_pk_bf16_f32 v166, v14, v15
	v_cvt_pk_bf16_f32 v167, v16, v17
	v_cvt_pk_bf16_f32 v168, v10, v11
	v_cvt_pk_bf16_f32 v169, v12, v13
	global_store_dwordx4 v190, v[166:169], s[10:11]
	s_andn2_b64 vcc, exec, s[8:9]
	s_mov_b64 s[4:5], -1
	s_branch .Lep_join
